# attention loops: wave-uniform fast path skips new-max/alpha/rescale-test when all lanes are within the defer-max threshold; on top of v37
# speedup vs baseline: 1.0004x; 1.0004x over previous
; #define SBAR() __builtin_amdgcn_sched_barrier(0)
; __device__ __forceinline__ void finishSM(f32x16& p0, f32x16& p1, float alpha, float& l_reg, bf16x8& pa0, bf16x8& pa1, bf16x8& pa2, bf16x8& pa3) {
; #pragma unroll
;   for (int r = 0; r < 16; ++r) p1[r] = __builtin_amdgcn_exp2f(p1[r]);
;   float ps = 0;
; #pragma unroll
;   for (int r = 0; r < 16; ++r) ps += p0[r];
; #pragma unroll
;   for (int r = 0; r < 16; ++r) ps += p1[r];
;   { auto rr = __builtin_amdgcn_permlane32_swap(__float_as_uint(ps), __float_as_uint(ps), false, false);
;     ps = __uint_as_float(rr[0]) + __uint_as_float(rr[1]); }
;   l_reg = l_reg * alpha + ps;
;     ...
;   PK4(p0, 0, pa0); PK4(p0, 8, pa1); PK4(p1, 0, pa2); PK4(p1, 8, pa3);
;     ...
; }
; template <int DK, int LDQ, int LDK, int LDV, int LDO, int SDEPTH, int NPARK>
; __device__ __forceinline__ void body(const bf16_t* __restrict__ Qb, const bf16_t* __restrict__ Kh, const bf16_t* __restrict__ Vh, bf16_t* __restrict__ Ob, int seq, char* lds, int tid, int wid) {
;     ...
;     SBAR(); qkt<DK, NPARK>(pB0, pB1, K_lds + SHM_K, qr, qpark, r32, hi);
;     finishSM(pA0, pA1, alA, l_reg, pa0, pa1, pa2, pa3); SBAR();
;     SLOAD(SO, (j + SDEPTH) * KVBLK); SBAR();
;     pv_d0(o, vb0, pa0, pa1, pa2, pa3); partialSM<DK>(pB0, pB1, m_reg, mnB, alB);
.LBB0_924:
	ds_read_b128 v[64:67], v161 offset:49152
	ds_read_b128 v[68:71], v161 offset:57344
	ds_read_b128 v[194:197], v170 offset:49152
	ds_read_b128 v[198:201], v170 offset:57344
	v_add_f32_e32 v144, v187, v145
	s_waitcnt lgkmcnt(3)
	v_mfma_f32_32x32x16_bf16 v[80:95], v[64:67], v[112:115], 0
	v_add_f32_e32 v144, v146, v144
	v_add_f32_e32 v144, v188, v144
	v_add_f32_e32 v144, v186, v144
	v_add_f32_e32 v144, v189, v144
	v_add_f32_e32 v144, v147, v144
	v_add_f32_e32 v144, v185, v144
	v_add_f32_e32 v144, v157, v144
	s_waitcnt lgkmcnt(2)
	v_mfma_f32_32x32x16_bf16 v[64:79], v[68:71], v[112:115], 0
	v_add_f32_e32 v144, v181, v144
	v_add_f32_e32 v144, v179, v144
	v_add_f32_e32 v144, v182, v144
	v_exp_f32_e32 v142, v142
	v_add_f32_e32 v144, v154, v144
	v_exp_f32_e32 v143, v143
	v_add_f32_e32 v144, v155, v144
	s_waitcnt lgkmcnt(1)
	v_mfma_f32_32x32x16_bf16 v[80:95], v[194:197], v[108:111], v[80:95]
	v_exp_f32_e32 v140, v140
	v_add_f32_e32 v144, v156, v144
	v_exp_f32_e32 v141, v141
	v_add_f32_e32 v144, v180, v144
	v_exp_f32_e32 v136, v136
	v_add_f32_e32 v144, v142, v144
	v_exp_f32_e32 v137, v137
	s_waitcnt lgkmcnt(0)
	v_mfma_f32_32x32x16_bf16 v[64:79], v[198:201], v[108:111], v[64:79]
	ds_read_b128 v[194:197], v169 offset:49152
	ds_read_b128 v[198:201], v169 offset:57344
	v_add_f32_e32 v144, v143, v144
	v_exp_f32_e32 v132, v132
	v_add_f32_e32 v144, v140, v144
	v_exp_f32_e32 v133, v133
	v_add_f32_e32 v144, v141, v144
	v_exp_f32_e32 v130, v130
	s_waitcnt lgkmcnt(1)
	v_mfma_f32_32x32x16_bf16 v[80:95], v[194:197], v[120:123], v[80:95]
	v_add_f32_e32 v144, v136, v144
	v_exp_f32_e32 v131, v131
	v_add_f32_e32 v144, v137, v144
	v_exp_f32_e32 v138, v138
	v_add_f32_e32 v144, v132, v144
	v_exp_f32_e32 v139, v139
	v_add_f32_e32 v144, v133, v144
	s_waitcnt lgkmcnt(0)
	v_mfma_f32_32x32x16_bf16 v[64:79], v[198:201], v[120:123], v[64:79]
	ds_read_b128 v[194:197], v168 offset:49152
	ds_read_b128 v[198:201], v168 offset:57344
	v_exp_f32_e32 v134, v134
	v_add_f32_e32 v144, v130, v144
	v_exp_f32_e32 v135, v135
	v_add_f32_e32 v144, v131, v144
	v_exp_f32_e32 v128, v128
	v_add_f32_e32 v144, v138, v144
	s_waitcnt lgkmcnt(1)
	v_mfma_f32_32x32x16_bf16 v[80:95], v[194:197], v[124:127], v[80:95]
	v_exp_f32_e32 v129, v129
	v_add_f32_e32 v144, v139, v144
	v_add_f32_e32 v144, v134, v144
	v_add_f32_e32 v144, v135, v144
	v_add_f32_e32 v144, v128, v144
	v_add_f32_e32 v175, v129, v144
	v_mov_b32_e32 v176, v175
	s_waitcnt lgkmcnt(0)
	v_mfma_f32_32x32x16_bf16 v[64:79], v[198:201], v[124:127], v[64:79]
	ds_read_b128 v[194:197], v167 offset:49152
	ds_read_b128 v[198:201], v167 offset:57344
	v_permlane32_swap_b32_e32 v175, v176
	s_waitcnt lgkmcnt(1)
	v_mfma_f32_32x32x16_bf16 v[80:95], v[194:197], v[116:119], v[80:95]
	s_waitcnt lgkmcnt(0)
	v_mfma_f32_32x32x16_bf16 v[64:79], v[198:201], v[116:119], v[64:79]
	ds_read_b128 v[194:197], v166 offset:49152
	ds_read_b128 v[198:201], v166 offset:57344
	s_waitcnt lgkmcnt(1)
	v_mfma_f32_32x32x16_bf16 v[80:95], v[194:197], v[104:107], v[80:95]
	s_waitcnt lgkmcnt(0)
	v_mfma_f32_32x32x16_bf16 v[64:79], v[198:201], v[104:107], v[64:79]
	ds_read_b128 v[194:197], v172 offset:49152
	ds_read_b128 v[198:201], v172 offset:57344
	s_waitcnt lgkmcnt(1)
	v_mfma_f32_32x32x16_bf16 v[80:95], v[194:197], v[100:103], v[80:95]
	s_waitcnt lgkmcnt(0)
	v_mfma_f32_32x32x16_bf16 v[64:79], v[198:201], v[100:103], v[64:79]
	ds_read_b128 v[194:197], v171 offset:49152
	ds_read_b128 v[198:201], v171 offset:57344
	v_cvt_pk_bf16_f32 v144, v145, v187
	v_cvt_pk_bf16_f32 v145, v146, v188
	v_cvt_pk_bf16_f32 v146, v186, v189
	v_cvt_pk_bf16_f32 v147, v147, v185
	v_cvt_pk_bf16_f32 v184, v157, v181
	v_cvt_pk_bf16_f32 v185, v179, v182
	s_waitcnt lgkmcnt(1)
	v_mfma_f32_32x32x16_bf16 v[80:95], v[194:197], v[96:99], v[80:95]
	v_permlane32_swap_b32_e32 v144, v146
	v_cvt_pk_bf16_f32 v186, v154, v155
	v_cvt_pk_bf16_f32 v187, v156, v180
	v_cvt_pk_bf16_f32 v180, v142, v143
	v_cvt_pk_bf16_f32 v181, v140, v141
	v_cvt_pk_bf16_f32 v182, v136, v137
	s_waitcnt lgkmcnt(0)
	v_mfma_f32_32x32x16_bf16 v[64:79], v[198:201], v[96:99], v[64:79]
	v_cvt_pk_bf16_f32 v183, v132, v133
	v_cvt_pk_bf16_f32 v188, v130, v131
	v_cvt_pk_bf16_f32 v189, v138, v139
	v_cvt_pk_bf16_f32 v190, v134, v135
	v_cvt_pk_bf16_f32 v191, v128, v129
	v_permlane32_swap_b32_e32 v145, v147
	v_permlane32_swap_b32_e32 v184, v186
	v_permlane32_swap_b32_e32 v185, v187
	v_permlane32_swap_b32_e32 v180, v182
	v_permlane32_swap_b32_e32 v181, v183
	v_permlane32_swap_b32_e32 v188, v190
	v_permlane32_swap_b32_e32 v189, v191
	s_add_u32 s46, s10, s0
	s_addc_u32 s47, s11, 0
	s_add_u32 s48, s10, s67
	s_addc_u32 s49, s11, 0
	global_load_dwordx4 v[128:131], v192, s[46:47]
	global_load_dwordx4 v[132:135], v152, s[46:47]
	global_load_dwordx4 v[136:139], v192, s[48:49]
	global_load_dwordx4 v[140:143], v152, s[48:49]
	ds_read_b64_tr_b16 v[194:195], v160 offset:0
	ds_read_b64_tr_b16 v[196:197], v160 offset:0x800
	ds_read_b64_tr_b16 v[198:199], v160 offset:0x1000
	ds_read_b64_tr_b16 v[200:201], v160 offset:0x1800
	ds_read_b64_tr_b16 v[202:203], v160 offset:0x2000
	ds_read_b64_tr_b16 v[204:205], v160 offset:0x2800
	ds_read_b64_tr_b16 v[206:207], v160 offset:0x3000
	ds_read_b64_tr_b16 v[208:209], v160 offset:0x3800
	s_waitcnt lgkmcnt(0)
	v_mfma_f32_32x32x16_bf16 v[0:15], v[144:147], v[194:197], v[0:15]
	ds_read_b64_tr_b16 v[194:195], v160 offset:0x200
	ds_read_b64_tr_b16 v[196:197], v160 offset:0xa00
	v_mfma_f32_32x32x16_bf16 v[0:15], v[184:187], v[198:201], v[0:15]
	ds_read_b64_tr_b16 v[198:199], v160 offset:0x1200
	ds_read_b64_tr_b16 v[200:201], v160 offset:0x1a00
	v_mfma_f32_32x32x16_bf16 v[0:15], v[180:183], v[202:205], v[0:15]
	ds_read_b64_tr_b16 v[202:203], v160 offset:0x2200
	ds_read_b64_tr_b16 v[204:205], v160 offset:0x2a00
	v_mfma_f32_32x32x16_bf16 v[0:15], v[188:191], v[206:209], v[0:15]
	ds_read_b64_tr_b16 v[206:207], v160 offset:0x3200
	ds_read_b64_tr_b16 v[208:209], v160 offset:0x3a00
	s_waitcnt lgkmcnt(0)
; #define SBAR() __builtin_amdgcn_sched_barrier(0)
; #define SWAIT() do { if constexpr (SDEPTH == 2) { if constexpr (DK == 192) asm volatile("s_waitcnt vmcnt(5)" ::: "memory"); else asm volatile("s_waitcnt vmcnt(4)" ::: "memory"); } else asm volatile("s_waitcnt vmcnt(0)" ::: "memory"); } while (0)
; template <int DK>
; __device__ __forceinline__ void partialSM(f32x16& p0, f32x16& p1, float& m_reg, float& mn, float& alpha) {
;   constexpr float SCALE = Cst<DK>::SCALE, C = SCALE * 1.4426950408889634f;
;   float pmax = p0[0];
; #pragma unroll
;   for (int r = 1; r < 16; ++r) pmax = fmaxf(pmax, p0[r]);
; #pragma unroll
;   for (int r = 0; r < 16; ++r) pmax = fmaxf(pmax, p1[r]);
;   { auto rr = __builtin_amdgcn_permlane32_swap(__float_as_uint(pmax), __float_as_uint(pmax), false, false);
;     pmax = fmaxf(__uint_as_float(rr[0]), __uint_as_float(rr[1])); }
;   if (__builtin_expect(__all(pmax - m_reg <= THR / SCALE), 1)) { mn = m_reg; alpha = 1.f; }
;   else { mn = fmaxf(m_reg, pmax); alpha = __builtin_amdgcn_exp2f((m_reg - mn) * C); m_reg = mn; }
; template <int DK, int LDQ, int LDK, int LDV, int LDO, int SDEPTH, int NPARK>
; __device__ __forceinline__ void body(const bf16_t* __restrict__ Qb, const bf16_t* __restrict__ Kh, const bf16_t* __restrict__ Vh, bf16_t* __restrict__ Ob, int seq, char* lds, int tid, int wid) {
;     ...
;   f32x16 pA0, pA1, pB0, pB1; float mnA, mnB, alA, alB; bf16x8 pa0, pa1, pa2, pa3; const int NT = seq / KVBLK;
;   constexpr int SE = 0, SO = SDEPTH - 1;
;   SLOAD(SE, 0); asm volatile("s_waitcnt vmcnt(0)" ::: "memory"); SWRITE(0, SE); __syncthreads();
;   qkt<DK, NPARK>(pA0, pA1, K_lds, qr, qpark, r32, hi); partialSM<DK>(pA0, pA1, m_reg, mnA, alA);
;   SLOAD(SO, KVBLK); if constexpr (SDEPTH == 2) { if (2 < NT) SLOAD(SE, 2 * KVBLK); }
;   SWAIT(); SWRITE(1, SO); __syncthreads();
;   for (int j = 1; j + 1 < NT; j += 2) {
;     SBAR(); qkt<DK, NPARK>(pB0, pB1, K_lds + SHM_K, qr, qpark, r32, hi);
;     finishSM(pA0, pA1, alA, l_reg, pa0, pa1, pa2, pa3); SBAR();
;     SLOAD(SO, (j + SDEPTH) * KVBLK); SBAR();
;     pv_d0(o, vb0, pa0, pa1, pa2, pa3); partialSM<DK>(pB0, pB1, m_reg, mnB, alB);
;     __syncthreads(); SWAIT(); SWRITE(0, SE);
;     RESC(alB); __syncthreads();
	v_mfma_f32_32x32x16_bf16 v[48:63], v[144:147], v[194:197], v[48:63]
	ds_read_b64_tr_b16 v[194:195], v160 offset:0x400
	ds_read_b64_tr_b16 v[196:197], v160 offset:0xc00
	v_mfma_f32_32x32x16_bf16 v[48:63], v[184:187], v[198:201], v[48:63]
	ds_read_b64_tr_b16 v[198:199], v160 offset:0x1400
	ds_read_b64_tr_b16 v[200:201], v160 offset:0x1c00
	v_mfma_f32_32x32x16_bf16 v[48:63], v[180:183], v[202:205], v[48:63]
	ds_read_b64_tr_b16 v[202:203], v160 offset:0x2400
	ds_read_b64_tr_b16 v[204:205], v160 offset:0x2c00
	v_mfma_f32_32x32x16_bf16 v[48:63], v[188:191], v[206:209], v[48:63]
	ds_read_b64_tr_b16 v[206:207], v160 offset:0x3400
	ds_read_b64_tr_b16 v[208:209], v160 offset:0x3c00
	s_waitcnt lgkmcnt(0)
	v_mfma_f32_32x32x16_bf16 v[32:47], v[144:147], v[194:197], v[32:47]
	ds_read_b64_tr_b16 v[194:195], v160 offset:0x600
	ds_read_b64_tr_b16 v[196:197], v160 offset:0xe00
	v_mfma_f32_32x32x16_bf16 v[32:47], v[184:187], v[198:201], v[32:47]
	ds_read_b64_tr_b16 v[198:199], v160 offset:0x1600
	ds_read_b64_tr_b16 v[200:201], v160 offset:0x1e00
	v_mfma_f32_32x32x16_bf16 v[32:47], v[180:183], v[202:205], v[32:47]
	ds_read_b64_tr_b16 v[202:203], v160 offset:0x2600
	ds_read_b64_tr_b16 v[204:205], v160 offset:0x2e00
	v_mfma_f32_32x32x16_bf16 v[32:47], v[188:191], v[206:209], v[32:47]
	ds_read_b64_tr_b16 v[206:207], v160 offset:0x3600
	ds_read_b64_tr_b16 v[208:209], v160 offset:0x3e00
	s_waitcnt lgkmcnt(0)
	v_mfma_f32_32x32x16_bf16 v[16:31], v[144:147], v[194:197], v[16:31]
	v_max_f32_e32 v144, v80, v81
	v_max3_f32 v144, v144, v82, v83
	v_max3_f32 v144, v144, v84, v85
	v_max3_f32 v144, v144, v86, v87
	v_max3_f32 v144, v144, v88, v89
	v_max3_f32 v144, v144, v90, v91
	v_max3_f32 v144, v144, v92, v93
	v_mfma_f32_32x32x16_bf16 v[16:31], v[184:187], v[198:201], v[16:31]
	v_max3_f32 v144, v144, v94, v95
	v_max3_f32 v144, v144, v64, v65
	v_max3_f32 v144, v144, v66, v67
	v_max3_f32 v144, v144, v68, v69
	v_max3_f32 v144, v144, v70, v71
	v_max3_f32 v144, v144, v72, v73
	v_max3_f32 v144, v144, v74, v75
	v_max3_f32 v144, v144, v76, v77
	v_mfma_f32_32x32x16_bf16 v[16:31], v[180:183], v[202:205], v[16:31]
	v_max3_f32 v144, v144, v78, v79
	v_mov_b32_e32 v145, v144
	s_nop 1
	v_permlane32_swap_b32_e32 v144, v145
	v_max_f32_e32 v144, v144, v145
	v_sub_f32_e32 v145, v144, v174
	v_cmp_ge_f32_e32 vcc, s1, v145
	v_mfma_f32_32x32x16_bf16 v[16:31], v[188:191], v[206:209], v[16:31]
	s_cmp_eq_u64 vcc, exec
	s_cselect_b64 s[8:9], -1, 0
	s_cbranch_scc1 .Lafast_1
	v_max_f32_e32 v144, v174, v144
	v_sub_f32_e32 v145, v174, v144
	v_mul_f32_e32 v145, 0x3e0293ee, v145
	v_exp_f32_e32 v145, v145
	s_barrier
	s_waitcnt vmcnt(0)
	v_cndmask_b32_e64 v177, v145, 1.0, s[8:9]
	v_cmp_gt_f32_e32 vcc, 1.0, v177
	ds_write_b128 v164, v[128:131]
	ds_write_b128 v165, v[132:135]
	ds_write_b128 v162, v[136:139] offset:32768
	ds_write_b128 v163, v[140:143] offset:32768
	s_cbranch_vccz .LBB0_928
	s_and_saveexec_b64 s[12:13], s[6:7]
	ds_write_b32 v151, v177 offset:128
	s_or_b64 exec, exec, s[12:13]
	s_waitcnt lgkmcnt(0)
	v_add_u32_e32 v140, s95, v150
	ds_read_b128 v[128:131], v140 offset:224
	ds_read_b128 v[132:135], v140 offset:192
	ds_read_b128 v[136:139], v140 offset:160
	ds_read_b128 v[140:143], v140 offset:128
	s_waitcnt lgkmcnt(3)
	v_pk_mul_f32 v[12:13], v[12:13], v[128:129]
	s_waitcnt lgkmcnt(2)
	v_pk_mul_f32 v[8:9], v[8:9], v[132:133]
	s_waitcnt lgkmcnt(1)
	v_pk_mul_f32 v[4:5], v[4:5], v[136:137]
	v_pk_mul_f32 v[14:15], v[14:15], v[130:131]
	v_pk_mul_f32 v[10:11], v[10:11], v[134:135]
	v_pk_mul_f32 v[6:7], v[6:7], v[138:139]
	s_waitcnt lgkmcnt(0)
	v_pk_mul_f32 v[2:3], v[2:3], v[142:143]
	v_pk_mul_f32 v[0:1], v[0:1], v[140:141]
	v_pk_mul_f32 v[60:61], v[60:61], v[128:129]
	v_pk_mul_f32 v[56:57], v[56:57], v[132:133]
	v_pk_mul_f32 v[52:53], v[52:53], v[136:137]
	v_pk_mul_f32 v[62:63], v[62:63], v[130:131]
	v_pk_mul_f32 v[58:59], v[58:59], v[134:135]
	v_pk_mul_f32 v[54:55], v[54:55], v[138:139]
	v_pk_mul_f32 v[50:51], v[50:51], v[142:143]
	v_pk_mul_f32 v[48:49], v[48:49], v[140:141]
	v_pk_mul_f32 v[44:45], v[44:45], v[128:129]
	v_pk_mul_f32 v[40:41], v[40:41], v[132:133]
	v_pk_mul_f32 v[36:37], v[36:37], v[136:137]
	v_pk_mul_f32 v[46:47], v[46:47], v[130:131]
	v_pk_mul_f32 v[42:43], v[42:43], v[134:135]
	v_pk_mul_f32 v[38:39], v[38:39], v[138:139]
	v_pk_mul_f32 v[34:35], v[34:35], v[142:143]
	v_pk_mul_f32 v[32:33], v[32:33], v[140:141]
	v_pk_mul_f32 v[28:29], v[28:29], v[128:129]
	v_pk_mul_f32 v[24:25], v[24:25], v[132:133]
	v_pk_mul_f32 v[20:21], v[20:21], v[136:137]
	v_pk_mul_f32 v[30:31], v[30:31], v[130:131]
	v_pk_mul_f32 v[26:27], v[26:27], v[134:135]
	v_pk_mul_f32 v[22:23], v[22:23], v[138:139]
	v_pk_mul_f32 v[18:19], v[18:19], v[142:143]
	v_pk_mul_f32 v[16:17], v[16:17], v[140:141]
.LBB0_928:
	v_cndmask_b32_e64 v174, v144, v174, s[8:9]
	s_branch .Lajoin_1
.Lafast_1:
	s_barrier
	s_waitcnt vmcnt(0)
	v_mov_b32_e32 v177, 1.0
	ds_write_b128 v164, v[128:131]
	ds_write_b128 v165, v[132:135]
	ds_write_b128 v162, v[136:139] offset:32768
	ds_write_b128 v163, v[140:143] offset:32768
; #define SBAR() __builtin_amdgcn_sched_barrier(0)
; #define RESC(a) do { if (__any((a) < 1.f)) { if (hi == 0) al_l[r32] = (a); asm volatile("s_waitcnt lgkmcnt(0)" ::: "memory"); \
;     _Pragma("unroll") for (int d = 0; d < 4; ++d) _Pragma("unroll") for (int r = 0; r < 16; ++r) o[d][r] *= al_l[crow(r, hi)]; } } while (0)
; template <int DK>
; __device__ __forceinline__ void partialSM(f32x16& p0, f32x16& p1, float& m_reg, float& mn, float& alpha) {
;     ...
;   float mnC = -mn * C;
; #pragma unroll
;   for (int r = 0; r < 16; ++r) p0[r] = fmaf(p0[r], C, mnC);
; #pragma unroll
;   for (int r = 0; r < 16; ++r) p1[r] = fmaf(p1[r], C, mnC);
; #pragma unroll
;   for (int r = 0; r < 16; ++r) p0[r] = __builtin_amdgcn_exp2f(p0[r]);
; }
; __device__ __forceinline__ void finishSM(f32x16& p0, f32x16& p1, float alpha, float& l_reg, bf16x8& pa0, bf16x8& pa1, bf16x8& pa2, bf16x8& pa3) {
; #pragma unroll
;   for (int r = 0; r < 16; ++r) p1[r] = __builtin_amdgcn_exp2f(p1[r]);
;   float ps = 0;
; #pragma unroll
;   for (int r = 0; r < 16; ++r) ps += p0[r];
; #pragma unroll
;   for (int r = 0; r < 16; ++r) ps += p1[r];
;   { auto rr = __builtin_amdgcn_permlane32_swap(__float_as_uint(ps), __float_as_uint(ps), false, false);
;     ps = __uint_as_float(rr[0]) + __uint_as_float(rr[1]); }
; template <int DK, int LDQ, int LDK, int LDV, int LDO, int SDEPTH, int NPARK>
; __device__ __forceinline__ void body(const bf16_t* __restrict__ Qb, const bf16_t* __restrict__ Kh, const bf16_t* __restrict__ Vh, bf16_t* __restrict__ Ob, int seq, char* lds, int tid, int wid) {
;     ...
;     RESC(alB); __syncthreads();
;     SBAR(); qkt<DK, NPARK>(pA0, pA1, K_lds, qr, qpark, r32, hi);
;     finishSM(pB0, pB1, alB, l_reg, pa0, pa1, pa2, pa3); SBAR();
.Lajoin_1:
	v_mul_f32_e32 v144, 0xbe0293ee, v174
	v_pk_fma_f32 v[80:81], v[80:81], s[76:77], v[144:145] op_sel_hi:[1,0,0]
	v_pk_fma_f32 v[82:83], v[82:83], s[76:77], v[144:145] op_sel_hi:[1,0,0]
	v_pk_fma_f32 v[84:85], v[84:85], s[76:77], v[144:145] op_sel_hi:[1,0,0]
	v_pk_fma_f32 v[86:87], v[86:87], s[76:77], v[144:145] op_sel_hi:[1,0,0]
	v_pk_fma_f32 v[88:89], v[88:89], s[76:77], v[144:145] op_sel_hi:[1,0,0]
	v_pk_fma_f32 v[90:91], v[90:91], s[76:77], v[144:145] op_sel_hi:[1,0,0]
	v_pk_fma_f32 v[92:93], v[92:93], s[76:77], v[144:145] op_sel_hi:[1,0,0]
	v_pk_fma_f32 v[94:95], v[94:95], s[76:77], v[144:145] op_sel_hi:[1,0,0]
	v_fmamk_f32 v184, v64, 0x3e0293ee, v144
	v_fmamk_f32 v185, v65, 0x3e0293ee, v144
	v_fmamk_f32 v186, v66, 0x3e0293ee, v144
	v_fmamk_f32 v187, v67, 0x3e0293ee, v144
	v_fmamk_f32 v188, v68, 0x3e0293ee, v144
	v_fmamk_f32 v146, v69, 0x3e0293ee, v144
	v_fmamk_f32 v147, v70, 0x3e0293ee, v144
	v_fmamk_f32 v179, v71, 0x3e0293ee, v144
	v_fmamk_f32 v180, v72, 0x3e0293ee, v144
	v_fmamk_f32 v181, v73, 0x3e0293ee, v144
	v_fmamk_f32 v182, v74, 0x3e0293ee, v144
	v_fmamk_f32 v183, v75, 0x3e0293ee, v144
	v_fmamk_f32 v145, v76, 0x3e0293ee, v144
	v_fmamk_f32 v189, v77, 0x3e0293ee, v144
	v_fmamk_f32 v190, v78, 0x3e0293ee, v144
	v_fmac_f32_e32 v144, 0x3e0293ee, v79
	v_exp_f32_e32 v141, v80
	v_exp_f32_e32 v143, v81
	v_exp_f32_e32 v139, v82
	v_exp_f32_e32 v142, v83
	v_exp_f32_e32 v138, v84
	v_exp_f32_e32 v140, v85
	v_exp_f32_e32 v136, v86
	v_exp_f32_e32 v137, v87
	v_exp_f32_e32 v133, v88
	v_exp_f32_e32 v135, v89
	v_exp_f32_e32 v132, v90
	v_exp_f32_e32 v134, v91
	v_exp_f32_e32 v129, v92
	v_exp_f32_e32 v131, v93
	v_exp_f32_e32 v128, v94
	v_exp_f32_e32 v130, v95
	s_waitcnt lgkmcnt(0)
	s_barrier
	ds_read_b128 v[64:67], v161 offset:32768
	ds_read_b128 v[68:71], v161 offset:40960
	ds_read_b128 v[194:197], v170 offset:32768
	ds_read_b128 v[198:201], v170 offset:40960
	v_exp_f32_e32 v203, v144
	s_waitcnt lgkmcnt(3)
	v_mfma_f32_32x32x16_bf16 v[80:95], v[64:67], v[112:115], 0
	v_add_f32_e32 v144, v143, v141
	v_add_f32_e32 v144, v139, v144
	v_add_f32_e32 v144, v142, v144
	v_add_f32_e32 v144, v138, v144
	v_add_f32_e32 v144, v140, v144
	v_add_f32_e32 v144, v136, v144
	v_add_f32_e32 v144, v137, v144
	s_waitcnt lgkmcnt(2)
	v_mfma_f32_32x32x16_bf16 v[64:79], v[68:71], v[112:115], 0
	v_add_f32_e32 v144, v133, v144
	v_add_f32_e32 v144, v135, v144
	v_add_f32_e32 v144, v132, v144
	v_add_f32_e32 v144, v134, v144
	v_exp_f32_e32 v191, v184
	v_add_f32_e32 v144, v129, v144
	v_exp_f32_e32 v185, v185
	s_waitcnt lgkmcnt(1)
	v_mfma_f32_32x32x16_bf16 v[80:95], v[194:197], v[108:111], v[80:95]
	v_add_f32_e32 v144, v131, v144
	v_add_f32_e32 v144, v128, v144
	v_add_f32_e32 v144, v130, v144
	v_add_f32_e32 v144, v191, v144
	v_add_f32_e32 v144, v185, v144
	v_exp_f32_e32 v179, v179
	v_exp_f32_e32 v180, v180
	s_waitcnt lgkmcnt(0)
	v_mfma_f32_32x32x16_bf16 v[64:79], v[198:201], v[108:111], v[64:79]
	ds_read_b128 v[194:197], v169 offset:32768
	ds_read_b128 v[198:201], v169 offset:40960
	v_exp_f32_e32 v181, v181
	v_exp_f32_e32 v182, v182
	v_exp_f32_e32 v202, v189
	v_exp_f32_e32 v190, v190
	s_waitcnt lgkmcnt(1)
	v_mfma_f32_32x32x16_bf16 v[80:95], v[194:197], v[120:123], v[80:95]
	s_waitcnt lgkmcnt(0)
	v_mfma_f32_32x32x16_bf16 v[64:79], v[198:201], v[120:123], v[64:79]
	ds_read_b128 v[194:197], v168 offset:32768
	ds_read_b128 v[198:201], v168 offset:40960
	s_waitcnt lgkmcnt(1)
	v_mfma_f32_32x32x16_bf16 v[80:95], v[194:197], v[124:127], v[80:95]
	s_waitcnt lgkmcnt(0)
	v_mfma_f32_32x32x16_bf16 v[64:79], v[198:201], v[124:127], v[64:79]
	ds_read_b128 v[194:197], v167 offset:32768
	ds_read_b128 v[198:201], v167 offset:40960
	s_waitcnt lgkmcnt(1)
	v_mfma_f32_32x32x16_bf16 v[80:95], v[194:197], v[116:119], v[80:95]
	s_waitcnt lgkmcnt(0)
	v_mfma_f32_32x32x16_bf16 v[64:79], v[198:201], v[116:119], v[64:79]
	ds_read_b128 v[194:197], v166 offset:32768
	ds_read_b128 v[198:201], v166 offset:40960
	s_waitcnt lgkmcnt(1)
	v_mfma_f32_32x32x16_bf16 v[80:95], v[194:197], v[104:107], v[80:95]
	s_waitcnt lgkmcnt(0)
	v_mfma_f32_32x32x16_bf16 v[64:79], v[198:201], v[104:107], v[64:79]
	ds_read_b128 v[194:197], v172 offset:32768
	ds_read_b128 v[198:201], v172 offset:40960
	s_waitcnt lgkmcnt(1)
	v_mfma_f32_32x32x16_bf16 v[80:95], v[194:197], v[100:103], v[80:95]
	s_waitcnt lgkmcnt(0)
	v_mfma_f32_32x32x16_bf16 v[64:79], v[198:201], v[100:103], v[64:79]
	ds_read_b128 v[194:197], v171 offset:32768
	ds_read_b128 v[198:201], v171 offset:40960
	s_waitcnt lgkmcnt(1)
	v_mfma_f32_32x32x16_bf16 v[80:95], v[194:197], v[96:99], v[80:95]
	v_exp_f32_e32 v195, v186
	v_exp_f32_e32 v196, v187
	v_exp_f32_e32 v197, v188
	v_add_f32_e32 v144, v195, v144
	v_add_f32_e32 v144, v196, v144
	v_add_f32_e32 v144, v197, v144
	s_waitcnt lgkmcnt(0)
; __device__ __forceinline__ void finishSM(f32x16& p0, f32x16& p1, float alpha, float& l_reg, bf16x8& pa0, bf16x8& pa1, bf16x8& pa2, bf16x8& pa3) {
; #pragma unroll
;   for (int r = 0; r < 16; ++r) p1[r] = __builtin_amdgcn_exp2f(p1[r]);
;   float ps = 0;
; #pragma unroll
;   for (int r = 0; r < 16; ++r) ps += p0[r];
; #pragma unroll
;   for (int r = 0; r < 16; ++r) ps += p1[r];
;   { auto rr = __builtin_amdgcn_permlane32_swap(__float_as_uint(ps), __float_as_uint(ps), false, false);
;     ps = __uint_as_float(rr[0]) + __uint_as_float(rr[1]); }
;   l_reg = l_reg * alpha + ps;
;     ...
;   PK4(p0, 0, pa0); PK4(p0, 8, pa1); PK4(p1, 0, pa2); PK4(p1, 8, pa3);
;     ...
; }
; template <int DK, int NPARK>
; __device__ __forceinline__ void qkt(f32x16& p0, f32x16& p1, const char* Ks, const bf16x8* qr, const char* qpark, int r32, int hi) {
;   p0 = f32x16{}; p1 = f32x16{};
; #pragma unroll
;   for (int d0 = 0; d0 < DK / 16; ++d0) { const int cb = (d0 * 16 + hi * 8) * 2;
;     bf16x8 b0 = *reinterpret_cast<const bf16x8*>(Ks + kswz<DK>(r32, cb));
;     bf16x8 b1 = *reinterpret_cast<const bf16x8*>(Ks + kswz<DK>(32 + r32, cb));
;     bf16x8 q;
;     if constexpr (NPARK > 0) { if (d0 >= DK / 16 - NPARK) q = *reinterpret_cast<const bf16x8*>(qpark + (d0 - (DK / 16 - NPARK)) * 1024); else q = qr[d0]; } else q = qr[d0];
;     p0 = __builtin_amdgcn_mfma_f32_32x32x16_bf16(b0, q, p0, 0, 0, 0);
;     p1 = __builtin_amdgcn_mfma_f32_32x32x16_bf16(b1, q, p1, 0, 0, 0); }
; }
; __device__ __forceinline__ int v_st(int k, int c) { const int kk = (k & ~0xC) | ((k & 4) << 1) | ((k & 8) >> 1); return ((kk >> 3) * 4 + (c >> 5)) * 512 + ((kk & 7) * 32 + (c & 31)) * 2; }
; __device__ __forceinline__ int v_rd_base(int lane) { return ((lane & 3) << 3) | (((lane >> 2) & 3) << 6) | (((lane >> 4) & 1) << 5) | (((lane >> 5) & 1) << 8); }
; template <int OFF> __device__ __forceinline__ s16x4 tr_read(int vb) {
;   s16x4 r; asm volatile("ds_read_b64_tr_b16 %0, %1 offset:%2" : "=&v"(r) : "v"(vb), "i"(OFF) : "memory"); return r;
; }
; template <int D0> __device__ __forceinline__ void pv_one(f32x16& od, int vb, bf16x8 pa0, bf16x8 pa1, bf16x8 pa2, bf16x8 pa3) {
;   const s16x4 l0 = tr_read<v_rd_off(D0, 0, 0)>(vb), h0 = tr_read<v_rd_off(D0, 0, 1)>(vb), l1 = tr_read<v_rd_off(D0, 1, 0)>(vb), h1 = tr_read<v_rd_off(D0, 1, 1)>(vb);
	v_mfma_f32_32x32x16_bf16 v[64:79], v[198:201], v[96:99], v[64:79]
	v_exp_f32_e32 v198, v146
	v_exp_f32_e32 v199, v147
	v_exp_f32_e32 v200, v183
	v_exp_f32_e32 v201, v145
	v_add_f32_e32 v144, v198, v144
	v_add_f32_e32 v144, v199, v144
	v_add_f32_e32 v144, v179, v144
	v_add_f32_e32 v144, v180, v144
	v_add_f32_e32 v144, v181, v144
	v_add_f32_e32 v144, v182, v144
	v_add_f32_e32 v144, v200, v144
	v_add_f32_e32 v144, v201, v144
	v_add_f32_e32 v144, v202, v144
	v_add_f32_e32 v144, v190, v144
	v_add_f32_e32 v183, v203, v144
	v_mov_b32_e32 v184, v183
	v_cvt_pk_bf16_f32 v144, v141, v143
	v_cvt_pk_bf16_f32 v145, v139, v142
	v_cvt_pk_bf16_f32 v146, v138, v140
	v_cvt_pk_bf16_f32 v147, v136, v137
	s_nop 1
	v_permlane32_swap_b32_e32 v183, v184
	v_permlane32_swap_b32_e32 v144, v146
	v_permlane32_swap_b32_e32 v145, v147
	v_cvt_pk_bf16_f32 v186, v133, v135
	v_cvt_pk_bf16_f32 v187, v132, v134
	v_cvt_pk_bf16_f32 v188, v129, v131
	v_cvt_pk_bf16_f32 v189, v128, v130
	v_cvt_pk_bf16_f32 v194, v191, v185
	v_cvt_pk_bf16_f32 v195, v195, v196
	v_cvt_pk_bf16_f32 v196, v197, v198
	v_cvt_pk_bf16_f32 v197, v199, v179
	v_cvt_pk_bf16_f32 v198, v180, v181
	v_cvt_pk_bf16_f32 v199, v182, v200
	v_cvt_pk_bf16_f32 v200, v201, v202
	v_cvt_pk_bf16_f32 v201, v190, v203
	s_nop 0
	v_permlane32_swap_b32_e32 v186, v188
	v_permlane32_swap_b32_e32 v187, v189
	v_permlane32_swap_b32_e32 v194, v196
	v_permlane32_swap_b32_e32 v195, v197
	v_permlane32_swap_b32_e32 v198, v200
	v_permlane32_swap_b32_e32 v199, v201
	s_add_u32 s46, s10, s61
	s_addc_u32 s47, s11, 0
	s_add_u32 s48, s10, s64
	s_addc_u32 s49, s11, 0
	global_load_dwordx4 v[128:131], v192, s[46:47]
	global_load_dwordx4 v[132:135], v152, s[46:47]
	global_load_dwordx4 v[136:139], v192, s[48:49]
	global_load_dwordx4 v[140:143], v152, s[48:49]
	ds_read_b64_tr_b16 v[154:155], v159 offset:0
	ds_read_b64_tr_b16 v[156:157], v159 offset:0x800
	ds_read_b64_tr_b16 v[202:203], v159 offset:0x1000
	ds_read_b64_tr_b16 v[204:205], v159 offset:0x1800
	ds_read_b64_tr_b16 v[206:207], v159 offset:0x2000
	ds_read_b64_tr_b16 v[208:209], v159 offset:0x2800
	ds_read_b64_tr_b16 v[210:211], v159 offset:0x3000
	ds_read_b64_tr_b16 v[212:213], v159 offset:0x3800
	s_waitcnt lgkmcnt(0)
	v_mfma_f32_32x32x16_bf16 v[0:15], v[144:147], v[154:157], v[0:15]
	ds_read_b64_tr_b16 v[154:155], v159 offset:0x200
	ds_read_b64_tr_b16 v[156:157], v159 offset:0xa00
	v_mfma_f32_32x32x16_bf16 v[0:15], v[186:189], v[202:205], v[0:15]
	ds_read_b64_tr_b16 v[202:203], v159 offset:0x1200
	ds_read_b64_tr_b16 v[204:205], v159 offset:0x1a00
	v_mfma_f32_32x32x16_bf16 v[0:15], v[194:197], v[206:209], v[0:15]
	ds_read_b64_tr_b16 v[206:207], v159 offset:0x2200
	ds_read_b64_tr_b16 v[208:209], v159 offset:0x2a00
	v_mfma_f32_32x32x16_bf16 v[0:15], v[198:201], v[210:213], v[0:15]
	ds_read_b64_tr_b16 v[210:211], v159 offset:0x3200
	ds_read_b64_tr_b16 v[212:213], v159 offset:0x3a00
	s_waitcnt lgkmcnt(0)
	v_mfma_f32_32x32x16_bf16 v[48:63], v[144:147], v[154:157], v[48:63]
	ds_read_b64_tr_b16 v[154:155], v159 offset:0x400
	ds_read_b64_tr_b16 v[156:157], v159 offset:0xc00
	v_mfma_f32_32x32x16_bf16 v[48:63], v[186:189], v[202:205], v[48:63]
	ds_read_b64_tr_b16 v[202:203], v159 offset:0x1400
	ds_read_b64_tr_b16 v[204:205], v159 offset:0x1c00
	v_mfma_f32_32x32x16_bf16 v[48:63], v[194:197], v[206:209], v[48:63]
	ds_read_b64_tr_b16 v[206:207], v159 offset:0x2400
	ds_read_b64_tr_b16 v[208:209], v159 offset:0x2c00
	v_mfma_f32_32x32x16_bf16 v[48:63], v[198:201], v[210:213], v[48:63]
	ds_read_b64_tr_b16 v[210:211], v159 offset:0x3400
	ds_read_b64_tr_b16 v[212:213], v159 offset:0x3c00
	s_waitcnt lgkmcnt(0)
	v_mfma_f32_32x32x16_bf16 v[32:47], v[144:147], v[154:157], v[32:47]
	ds_read_b64_tr_b16 v[154:155], v159 offset:0x600
	ds_read_b64_tr_b16 v[156:157], v159 offset:0xe00
	v_mfma_f32_32x32x16_bf16 v[32:47], v[186:189], v[202:205], v[32:47]
	ds_read_b64_tr_b16 v[202:203], v159 offset:0x1600
	ds_read_b64_tr_b16 v[204:205], v159 offset:0x1e00
	v_mfma_f32_32x32x16_bf16 v[32:47], v[194:197], v[206:209], v[32:47]
	ds_read_b64_tr_b16 v[206:207], v159 offset:0x2600
	ds_read_b64_tr_b16 v[208:209], v159 offset:0x2e00
	v_mfma_f32_32x32x16_bf16 v[32:47], v[198:201], v[210:213], v[32:47]
	ds_read_b64_tr_b16 v[210:211], v159 offset:0x3600
	ds_read_b64_tr_b16 v[212:213], v159 offset:0x3e00
	s_waitcnt lgkmcnt(0)
	v_mfma_f32_32x32x16_bf16 v[16:31], v[144:147], v[154:157], v[16:31]
	v_max_f32_e32 v144, v80, v81
	v_max3_f32 v144, v144, v82, v83
	v_max3_f32 v144, v144, v84, v85
	v_max3_f32 v144, v144, v86, v87
	v_max3_f32 v144, v144, v88, v89
	v_max3_f32 v144, v144, v90, v91
	v_max3_f32 v144, v144, v92, v93
	v_mfma_f32_32x32x16_bf16 v[16:31], v[186:189], v[202:205], v[16:31]
	v_max3_f32 v144, v144, v94, v95
	v_max3_f32 v144, v144, v64, v65
	v_max3_f32 v144, v144, v66, v67
	v_max3_f32 v144, v144, v68, v69
	v_max3_f32 v144, v144, v70, v71
	v_max3_f32 v144, v144, v72, v73
	v_max3_f32 v144, v144, v74, v75
	v_max3_f32 v144, v144, v76, v77
	v_mfma_f32_32x32x16_bf16 v[16:31], v[194:197], v[206:209], v[16:31]
	v_max3_f32 v144, v144, v78, v79
	v_mov_b32_e32 v145, v144
	s_nop 1
	v_permlane32_swap_b32_e32 v144, v145
	v_max_f32_e32 v144, v144, v145
	v_sub_f32_e32 v145, v144, v174
	v_cmp_ge_f32_e32 vcc, s1, v145
	v_mfma_f32_32x32x16_bf16 v[16:31], v[198:201], v[210:213], v[16:31]
	s_cmp_eq_u64 vcc, exec
	s_cselect_b64 s[8:9], -1, 0
	s_cbranch_scc1 .Lafast_2
; #define SBAR() __builtin_amdgcn_sched_barrier(0)
; #define SWAIT() do { if constexpr (SDEPTH == 2) { if constexpr (DK == 192) asm volatile("s_waitcnt vmcnt(5)" ::: "memory"); else asm volatile("s_waitcnt vmcnt(4)" ::: "memory"); } else asm volatile("s_waitcnt vmcnt(0)" ::: "memory"); } while (0)
; #define RESC(a) do { if (__any((a) < 1.f)) { if (hi == 0) al_l[r32] = (a); asm volatile("s_waitcnt lgkmcnt(0)" ::: "memory"); \
;     _Pragma("unroll") for (int d = 0; d < 4; ++d) _Pragma("unroll") for (int r = 0; r < 16; ++r) o[d][r] *= al_l[crow(r, hi)]; } } while (0)
; template <int DK>
; __device__ __forceinline__ void partialSM(f32x16& p0, f32x16& p1, float& m_reg, float& mn, float& alpha) {
;   constexpr float SCALE = Cst<DK>::SCALE, C = SCALE * 1.4426950408889634f;
;   float pmax = p0[0];
; #pragma unroll
;   for (int r = 1; r < 16; ++r) pmax = fmaxf(pmax, p0[r]);
; #pragma unroll
;   for (int r = 0; r < 16; ++r) pmax = fmaxf(pmax, p1[r]);
;   { auto rr = __builtin_amdgcn_permlane32_swap(__float_as_uint(pmax), __float_as_uint(pmax), false, false);
;     pmax = fmaxf(__uint_as_float(rr[0]), __uint_as_float(rr[1])); }
;   if (__builtin_expect(__all(pmax - m_reg <= THR / SCALE), 1)) { mn = m_reg; alpha = 1.f; }
;   else { mn = fmaxf(m_reg, pmax); alpha = __builtin_amdgcn_exp2f((m_reg - mn) * C); m_reg = mn; }
;   float mnC = -mn * C;
; #pragma unroll
;   for (int r = 0; r < 16; ++r) p0[r] = fmaf(p0[r], C, mnC);
; #pragma unroll
;   for (int r = 0; r < 16; ++r) p1[r] = fmaf(p1[r], C, mnC);
; #pragma unroll
;   for (int r = 0; r < 16; ++r) p0[r] = __builtin_amdgcn_exp2f(p0[r]);
; }
; template <int DK, int LDQ, int LDK, int LDV, int LDO, int SDEPTH, int NPARK>
; __device__ __forceinline__ void body(const bf16_t* __restrict__ Qb, const bf16_t* __restrict__ Kh, const bf16_t* __restrict__ Vh, bf16_t* __restrict__ Ob, int seq, char* lds, int tid, int wid) {
;     ...
;     __syncthreads(); SWAIT(); SWRITE(0, SE);
;     RESC(alB); __syncthreads();
;     SBAR(); qkt<DK, NPARK>(pA0, pA1, K_lds, qr, qpark, r32, hi);
;     finishSM(pB0, pB1, alB, l_reg, pa0, pa1, pa2, pa3); SBAR();
;     if (SDEPTH == 1 || j + 3 < NT) SLOAD(SE, (j + 1 + SDEPTH) * KVBLK); SBAR();
;     pv_d0(o, vb0 + (int)SHM_V, pa0, pa1, pa2, pa3); partialSM<DK>(pA0, pA1, m_reg, mnA, alA);
;     __syncthreads(); SWAIT(); SWRITE(1, SO);
;     RESC(alA); __syncthreads();
	v_max_f32_e32 v145, v174, v144
	v_sub_f32_e32 v144, v174, v145
	v_mul_f32_e32 v144, 0x3e0293ee, v144
	v_exp_f32_e32 v144, v144
	s_barrier
	s_waitcnt vmcnt(0)
	v_cndmask_b32_e64 v144, v144, 1.0, s[8:9]
	v_cmp_gt_f32_e32 vcc, 1.0, v144
	ds_write_b128 v164, v[128:131] offset:16384
	ds_write_b128 v165, v[132:135] offset:16384
	ds_write_b128 v162, v[136:139] offset:49152
	ds_write_b128 v163, v[140:143] offset:49152
	s_cbranch_vccz .LBB0_932
	s_and_saveexec_b64 s[12:13], s[6:7]
	ds_write_b32 v151, v144 offset:128
	s_or_b64 exec, exec, s[12:13]
	s_waitcnt lgkmcnt(0)
	v_add_u32_e32 v140, s95, v150
	ds_read_b128 v[128:131], v140 offset:224
	ds_read_b128 v[132:135], v140 offset:192
	ds_read_b128 v[136:139], v140 offset:160
	ds_read_b128 v[140:143], v140 offset:128
	s_waitcnt lgkmcnt(3)
	v_pk_mul_f32 v[12:13], v[12:13], v[128:129]
	s_waitcnt lgkmcnt(2)
	v_pk_mul_f32 v[8:9], v[8:9], v[132:133]
	s_waitcnt lgkmcnt(1)
	v_pk_mul_f32 v[4:5], v[4:5], v[136:137]
	v_pk_mul_f32 v[14:15], v[14:15], v[130:131]
	v_pk_mul_f32 v[10:11], v[10:11], v[134:135]
	v_pk_mul_f32 v[6:7], v[6:7], v[138:139]
	s_waitcnt lgkmcnt(0)
	v_pk_mul_f32 v[2:3], v[2:3], v[142:143]
	v_pk_mul_f32 v[0:1], v[0:1], v[140:141]
	v_pk_mul_f32 v[60:61], v[60:61], v[128:129]
	v_pk_mul_f32 v[56:57], v[56:57], v[132:133]
	v_pk_mul_f32 v[52:53], v[52:53], v[136:137]
	v_pk_mul_f32 v[62:63], v[62:63], v[130:131]
	v_pk_mul_f32 v[58:59], v[58:59], v[134:135]
	v_pk_mul_f32 v[54:55], v[54:55], v[138:139]
	v_pk_mul_f32 v[50:51], v[50:51], v[142:143]
	v_pk_mul_f32 v[48:49], v[48:49], v[140:141]
	v_pk_mul_f32 v[44:45], v[44:45], v[128:129]
	v_pk_mul_f32 v[40:41], v[40:41], v[132:133]
	v_pk_mul_f32 v[36:37], v[36:37], v[136:137]
	v_pk_mul_f32 v[46:47], v[46:47], v[130:131]
	v_pk_mul_f32 v[42:43], v[42:43], v[134:135]
	v_pk_mul_f32 v[38:39], v[38:39], v[138:139]
	v_pk_mul_f32 v[34:35], v[34:35], v[142:143]
	v_pk_mul_f32 v[32:33], v[32:33], v[140:141]
	v_pk_mul_f32 v[28:29], v[28:29], v[128:129]
	v_pk_mul_f32 v[24:25], v[24:25], v[132:133]
	v_pk_mul_f32 v[20:21], v[20:21], v[136:137]
	v_pk_mul_f32 v[30:31], v[30:31], v[130:131]
	v_pk_mul_f32 v[26:27], v[26:27], v[134:135]
	v_pk_mul_f32 v[22:23], v[22:23], v[138:139]
	v_pk_mul_f32 v[18:19], v[18:19], v[142:143]
	v_pk_mul_f32 v[16:17], v[16:17], v[140:141]
.LBB0_932:
	v_cndmask_b32_e64 v174, v145, v174, s[8:9]
	s_branch .Lajoin_2
.Lafast_2:
	s_barrier
	s_waitcnt vmcnt(0)
	v_mov_b32_e32 v144, 1.0
	ds_write_b128 v164, v[128:131] offset:16384
	ds_write_b128 v165, v[132:135] offset:16384
	ds_write_b128 v162, v[136:139] offset:49152
	ds_write_b128 v163, v[140:143] offset:49152
.Lajoin_2:
	v_mul_f32_e32 v128, 0xbe0293ee, v174
	v_pk_fma_f32 v[80:81], v[80:81], s[76:77], v[128:129] op_sel_hi:[1,0,0]
	v_pk_fma_f32 v[82:83], v[82:83], s[76:77], v[128:129] op_sel_hi:[1,0,0]
	v_pk_fma_f32 v[84:85], v[84:85], s[76:77], v[128:129] op_sel_hi:[1,0,0]
	v_pk_fma_f32 v[86:87], v[86:87], s[76:77], v[128:129] op_sel_hi:[1,0,0]
	v_pk_fma_f32 v[88:89], v[88:89], s[76:77], v[128:129] op_sel_hi:[1,0,0]
	v_pk_fma_f32 v[90:91], v[90:91], s[76:77], v[128:129] op_sel_hi:[1,0,0]
	v_pk_fma_f32 v[92:93], v[92:93], s[76:77], v[128:129] op_sel_hi:[1,0,0]
	v_pk_fma_f32 v[94:95], v[94:95], s[76:77], v[128:129] op_sel_hi:[1,0,0]
	v_exp_f32_e32 v145, v80
	v_exp_f32_e32 v187, v81
	v_exp_f32_e32 v146, v82
	v_exp_f32_e32 v188, v83
	v_exp_f32_e32 v186, v84
	v_exp_f32_e32 v189, v85
	v_exp_f32_e32 v147, v86
	v_exp_f32_e32 v185, v87
	v_exp_f32_e32 v157, v88
	v_exp_f32_e32 v181, v89
	v_exp_f32_e32 v179, v90
	v_exp_f32_e32 v182, v91
	v_exp_f32_e32 v154, v92
	v_exp_f32_e32 v155, v93
	v_exp_f32_e32 v156, v94
	v_exp_f32_e32 v180, v95
	v_pk_fma_f32 v[142:143], v[64:65], s[76:77], v[128:129] op_sel_hi:[1,0,0]
	v_add_f32_e32 v64, v175, v176
	s_add_u32 s10, s10, 0x10000
	v_fmac_f32_e32 v64, v173, v158
	v_add_f32_e32 v158, v183, v184
	s_addc_u32 s11, s11, 0
	s_add_i32 s14, s14, 2
	v_pk_fma_f32 v[140:141], v[66:67], s[76:77], v[128:129] op_sel_hi:[1,0,0]
	v_pk_fma_f32 v[136:137], v[68:69], s[76:77], v[128:129] op_sel_hi:[1,0,0]
	v_pk_fma_f32 v[132:133], v[70:71], s[76:77], v[128:129] op_sel_hi:[1,0,0]
	v_pk_fma_f32 v[130:131], v[72:73], s[76:77], v[128:129] op_sel_hi:[1,0,0]
	v_pk_fma_f32 v[138:139], v[74:75], s[76:77], v[128:129] op_sel_hi:[1,0,0]
	v_pk_fma_f32 v[134:135], v[76:77], s[76:77], v[128:129] op_sel_hi:[1,0,0]
	v_pk_fma_f32 v[128:129], v[78:79], s[76:77], v[128:129] op_sel_hi:[1,0,0]
	v_fmac_f32_e32 v158, v64, v177
	s_cmp_ge_u32 s14, s43
	s_waitcnt lgkmcnt(0)
	s_barrier
	s_cbranch_scc1 .LBB0_934
	v_mov_b32_e32 v173, v144
	s_branch .LBB0_924

; __device__ __forceinline__ void finishSM(f32x16& p0, f32x16& p1, float alpha, float& l_reg, bf16x8& pa0, bf16x8& pa1, bf16x8& pa2, bf16x8& pa3) {
; #pragma unroll
;   for (int r = 0; r < 16; ++r) p1[r] = __builtin_amdgcn_exp2f(p1[r]);
;   float ps = 0;
; #pragma unroll
;   for (int r = 0; r < 16; ++r) ps += p0[r];
; #pragma unroll
;   for (int r = 0; r < 16; ++r) ps += p1[r];
;   { auto rr = __builtin_amdgcn_permlane32_swap(__float_as_uint(ps), __float_as_uint(ps), false, false);
;     ps = __uint_as_float(rr[0]) + __uint_as_float(rr[1]); }
;   l_reg = l_reg * alpha + ps;
;     ...
;   PK4(p0, 0, pa0); PK4(p0, 8, pa1); PK4(p1, 0, pa2); PK4(p1, 8, pa3);
;     ...
; }
; template <int DK, int NPARK>
; __device__ __forceinline__ void qkt(f32x16& p0, f32x16& p1, const char* Ks, const bf16x8* qr, const char* qpark, int r32, int hi) {
;   p0 = f32x16{}; p1 = f32x16{};
; #pragma unroll
;   for (int d0 = 0; d0 < DK / 16; ++d0) { const int cb = (d0 * 16 + hi * 8) * 2;
;     bf16x8 b0 = *reinterpret_cast<const bf16x8*>(Ks + kswz<DK>(r32, cb));
;     bf16x8 b1 = *reinterpret_cast<const bf16x8*>(Ks + kswz<DK>(32 + r32, cb));
;     bf16x8 q;
;     if constexpr (NPARK > 0) { if (d0 >= DK / 16 - NPARK) q = *reinterpret_cast<const bf16x8*>(qpark + (d0 - (DK / 16 - NPARK)) * 1024); else q = qr[d0]; } else q = qr[d0];
;     p0 = __builtin_amdgcn_mfma_f32_32x32x16_bf16(b0, q, p0, 0, 0, 0);
;     p1 = __builtin_amdgcn_mfma_f32_32x32x16_bf16(b1, q, p1, 0, 0, 0); }
; }
.LBB0_948:
	ds_read_b128 v[64:67], v196 offset:57344
	ds_read_b128 v[68:71], v216 offset:57344
	ds_read_b128 v[174:177], v199 offset:57344
	ds_read_b128 v[218:221], v214 offset:57344
	v_add_f32_e32 v148, v170, v149
	s_waitcnt lgkmcnt(3)
	v_mfma_f32_32x32x16_bf16 v[80:95], v[64:67], v[124:127], 0
	v_add_f32_e32 v148, v150, v148
	v_add_f32_e32 v148, v171, v148
	v_add_f32_e32 v148, v169, v148
	v_add_f32_e32 v148, v172, v148
	v_add_f32_e32 v148, v151, v148
	v_add_f32_e32 v148, v168, v148
	v_add_f32_e32 v148, v147, v148
	s_waitcnt lgkmcnt(2)
	v_mfma_f32_32x32x16_bf16 v[64:79], v[68:71], v[124:127], 0
	v_add_f32_e32 v148, v152, v148
	v_add_f32_e32 v148, v153, v148
	v_add_f32_e32 v148, v154, v148
	v_exp_f32_e32 v142, v142
	v_add_f32_e32 v148, v144, v148
	v_exp_f32_e32 v143, v143
	v_add_f32_e32 v148, v145, v148
	s_waitcnt lgkmcnt(1)
	v_mfma_f32_32x32x16_bf16 v[80:95], v[174:177], v[116:119], v[80:95]
	v_exp_f32_e32 v140, v140
	v_add_f32_e32 v148, v146, v148
	v_exp_f32_e32 v141, v141
	v_add_f32_e32 v148, v155, v148
	v_exp_f32_e32 v136, v136
	v_add_f32_e32 v148, v142, v148
	v_exp_f32_e32 v137, v137
	s_waitcnt lgkmcnt(0)
	v_mfma_f32_32x32x16_bf16 v[64:79], v[218:221], v[116:119], v[64:79]
	ds_read_b128 v[174:177], v198 offset:57344
	ds_read_b128 v[218:221], v213 offset:57344
	v_add_f32_e32 v148, v143, v148
	v_exp_f32_e32 v132, v132
	v_add_f32_e32 v148, v140, v148
	v_exp_f32_e32 v133, v133
	v_add_f32_e32 v148, v141, v148
	v_exp_f32_e32 v130, v130
	s_waitcnt lgkmcnt(1)
	v_mfma_f32_32x32x16_bf16 v[80:95], v[174:177], v[120:123], v[80:95]
	v_add_f32_e32 v148, v136, v148
	v_exp_f32_e32 v131, v131
	v_add_f32_e32 v148, v137, v148
	v_exp_f32_e32 v138, v138
	v_add_f32_e32 v148, v132, v148
	v_exp_f32_e32 v139, v139
	v_add_f32_e32 v148, v133, v148
	s_waitcnt lgkmcnt(0)
	v_mfma_f32_32x32x16_bf16 v[64:79], v[218:221], v[120:123], v[64:79]
	ds_read_b128 v[174:177], v197 offset:57344
	ds_read_b128 v[218:221], v212 offset:57344
	v_exp_f32_e32 v134, v134
	v_add_f32_e32 v148, v130, v148
	v_exp_f32_e32 v135, v135
	v_add_f32_e32 v148, v131, v148
	v_exp_f32_e32 v128, v128
	v_add_f32_e32 v148, v138, v148
	s_waitcnt lgkmcnt(1)
	v_mfma_f32_32x32x16_bf16 v[80:95], v[174:177], v[112:115], v[80:95]
	v_exp_f32_e32 v129, v129
	v_add_f32_e32 v148, v139, v148
	v_add_f32_e32 v148, v134, v148
	v_add_f32_e32 v148, v135, v148
	v_add_f32_e32 v148, v128, v148
	v_add_f32_e32 v217, v129, v148
	s_waitcnt lgkmcnt(0)
	v_mfma_f32_32x32x16_bf16 v[64:79], v[218:221], v[112:115], v[64:79]
	ds_read_b128 v[174:177], v195 offset:57344
	ds_read_b128 v[218:221], v211 offset:57344
	s_waitcnt lgkmcnt(1)
	v_mfma_f32_32x32x16_bf16 v[80:95], v[174:177], v[108:111], v[80:95]
	s_waitcnt lgkmcnt(0)
	v_mfma_f32_32x32x16_bf16 v[64:79], v[218:221], v[108:111], v[64:79]
	ds_read_b128 v[174:177], v194 offset:57344
	ds_read_b128 v[218:221], v209 offset:57344
	s_waitcnt lgkmcnt(1)
	v_mfma_f32_32x32x16_bf16 v[80:95], v[174:177], v[104:107], v[80:95]
	s_waitcnt lgkmcnt(0)
	v_mfma_f32_32x32x16_bf16 v[64:79], v[218:221], v[104:107], v[64:79]
	ds_read_b128 v[174:177], v188 offset:57344
	ds_read_b128 v[218:221], v208 offset:57344
	s_waitcnt lgkmcnt(1)
	v_mfma_f32_32x32x16_bf16 v[80:95], v[174:177], v[100:103], v[80:95]
	s_waitcnt lgkmcnt(0)
	v_mfma_f32_32x32x16_bf16 v[64:79], v[218:221], v[100:103], v[64:79]
	ds_read_b128 v[174:177], v187 offset:57344
	ds_read_b128 v[218:221], v207 offset:57344
	s_waitcnt lgkmcnt(1)
	v_mfma_f32_32x32x16_bf16 v[80:95], v[174:177], v[96:99], v[80:95]
	s_waitcnt lgkmcnt(0)
	v_mfma_f32_32x32x16_bf16 v[64:79], v[218:221], v[96:99], v[64:79]
	ds_read_b128 v[174:177], v186 offset:57344
	ds_read_b128 v[218:221], v206 offset:57344
	ds_read_b128 v[222:225], v183
	s_waitcnt lgkmcnt(0)
	v_mfma_f32_32x32x16_bf16 v[80:95], v[174:177], v[222:225], v[80:95]
	v_mfma_f32_32x32x16_bf16 v[64:79], v[218:221], v[222:225], v[64:79]
	ds_read_b128 v[174:177], v190 offset:57344
	ds_read_b128 v[218:221], v205 offset:57344
	ds_read_b128 v[222:225], v183 offset:1024
	s_waitcnt lgkmcnt(0)
	v_mfma_f32_32x32x16_bf16 v[80:95], v[174:177], v[222:225], v[80:95]
	v_mfma_f32_32x32x16_bf16 v[64:79], v[218:221], v[222:225], v[64:79]
	ds_read_b128 v[174:177], v201 offset:57344
	ds_read_b128 v[218:221], v204 offset:57344
	ds_read_b128 v[222:225], v183 offset:2048
	s_waitcnt lgkmcnt(0)
	v_mfma_f32_32x32x16_bf16 v[80:95], v[174:177], v[222:225], v[80:95]
	v_mfma_f32_32x32x16_bf16 v[64:79], v[218:221], v[222:225], v[64:79]
	ds_read_b128 v[174:177], v200 offset:57344
	ds_read_b128 v[218:221], v203 offset:57344
	ds_read_b128 v[222:225], v183 offset:3072
	v_cvt_pk_bf16_f32 v148, v149, v170
	v_cvt_pk_bf16_f32 v149, v150, v171
	v_cvt_pk_bf16_f32 v150, v169, v172
	v_cvt_pk_bf16_f32 v151, v151, v168
	v_cvt_pk_bf16_f32 v152, v147, v152
	v_cvt_pk_bf16_f32 v153, v153, v154
	s_waitcnt lgkmcnt(0)
	v_mfma_f32_32x32x16_bf16 v[80:95], v[174:177], v[222:225], v[80:95]
	v_permlane32_swap_b32_e32 v148, v150
	v_cvt_pk_bf16_f32 v154, v144, v145
	v_cvt_pk_bf16_f32 v155, v146, v155
	v_permlane32_swap_b32_e32 v149, v151
	v_permlane32_swap_b32_e32 v152, v154
	v_mfma_f32_32x32x16_bf16 v[64:79], v[218:221], v[222:225], v[64:79]
	v_mov_b32_e32 v218, v217
	s_nop 1
	v_permlane32_swap_b32_e32 v217, v218
	v_cvt_pk_bf16_f32 v220, v142, v143
	v_cvt_pk_bf16_f32 v221, v140, v141
	v_cvt_pk_bf16_f32 v222, v136, v137
	v_cvt_pk_bf16_f32 v223, v132, v133
	v_cvt_pk_bf16_f32 v224, v130, v131
	v_cvt_pk_bf16_f32 v225, v138, v139
	v_cvt_pk_bf16_f32 v226, v134, v135
	v_cvt_pk_bf16_f32 v227, v128, v129
	v_permlane32_swap_b32_e32 v153, v155
	v_permlane32_swap_b32_e32 v220, v222
	v_permlane32_swap_b32_e32 v221, v223
	v_permlane32_swap_b32_e32 v224, v226
	v_permlane32_swap_b32_e32 v225, v227
	s_add_u32 s34, s32, s38
	s_addc_u32 s35, s33, 0
	s_add_u32 s36, s56, s39
	s_addc_u32 s37, s57, 0
	global_load_dwordx4 v[128:131], v251, s[34:35]
	global_load_dwordx4 v[132:135], v252, s[34:35]
	global_load_dwordx4 v[136:139], v248, s[36:37]
	global_load_dwordx4 v[140:143], v249, s[36:37]
	global_load_dwordx4 v[144:147], v250, s[36:37]
	ds_read_b64_tr_b16 v[228:229], v182 offset:0
	ds_read_b64_tr_b16 v[230:231], v182 offset:0x800
	ds_read_b64_tr_b16 v[232:233], v182 offset:0x1000
	ds_read_b64_tr_b16 v[234:235], v182 offset:0x1800
	ds_read_b64_tr_b16 v[236:237], v182 offset:0x2000
	ds_read_b64_tr_b16 v[238:239], v182 offset:0x2800
	ds_read_b64_tr_b16 v[244:245], v182 offset:0x3000
	ds_read_b64_tr_b16 v[246:247], v182 offset:0x3800
	s_waitcnt lgkmcnt(0)
; #define SBAR() __builtin_amdgcn_sched_barrier(0)
; template <int DK>
; __device__ __forceinline__ void partialSM(f32x16& p0, f32x16& p1, float& m_reg, float& mn, float& alpha) {
;   constexpr float SCALE = Cst<DK>::SCALE, C = SCALE * 1.4426950408889634f;
;   float pmax = p0[0];
; #pragma unroll
;   for (int r = 1; r < 16; ++r) pmax = fmaxf(pmax, p0[r]);
; #pragma unroll
;   for (int r = 0; r < 16; ++r) pmax = fmaxf(pmax, p1[r]);
;   { auto rr = __builtin_amdgcn_permlane32_swap(__float_as_uint(pmax), __float_as_uint(pmax), false, false);
;     pmax = fmaxf(__uint_as_float(rr[0]), __uint_as_float(rr[1])); }
;   if (__builtin_expect(__all(pmax - m_reg <= THR / SCALE), 1)) { mn = m_reg; alpha = 1.f; }
;   else { mn = fmaxf(m_reg, pmax); alpha = __builtin_amdgcn_exp2f((m_reg - mn) * C); m_reg = mn; }
; template <int D0> __device__ __forceinline__ void pv_one(f32x16& od, int vb, bf16x8 pa0, bf16x8 pa1, bf16x8 pa2, bf16x8 pa3) {
;   const s16x4 l0 = tr_read<v_rd_off(D0, 0, 0)>(vb), h0 = tr_read<v_rd_off(D0, 0, 1)>(vb), l1 = tr_read<v_rd_off(D0, 1, 0)>(vb), h1 = tr_read<v_rd_off(D0, 1, 1)>(vb);
;   const s16x4 l2 = tr_read<v_rd_off(D0, 2, 0)>(vb), h2 = tr_read<v_rd_off(D0, 2, 1)>(vb), l3 = tr_read<v_rd_off(D0, 3, 0)>(vb), h3 = tr_read<v_rd_off(D0, 3, 1)>(vb);
;   asm volatile("s_waitcnt lgkmcnt(0)" ::: "memory"); SBAR();
;     ...
;   od = __builtin_amdgcn_mfma_f32_32x32x16_bf16(pa0, PK(l0, h0), od, 0, 0, 0);
;   od = __builtin_amdgcn_mfma_f32_32x32x16_bf16(pa1, PK(l1, h1), od, 0, 0, 0);
;   od = __builtin_amdgcn_mfma_f32_32x32x16_bf16(pa2, PK(l2, h2), od, 0, 0, 0);
;   od = __builtin_amdgcn_mfma_f32_32x32x16_bf16(pa3, PK(l3, h3), od, 0, 0, 0);
;     ...
; }
; __device__ __forceinline__ void pv_d0(f32x16* o, int vb, bf16x8 pa0, bf16x8 pa1, bf16x8 pa2, bf16x8 pa3) {
;   pv_one<0>(o[0], vb, pa0, pa1, pa2, pa3); pv_one<1>(o[1], vb, pa0, pa1, pa2, pa3); pv_one<2>(o[2], vb, pa0, pa1, pa2, pa3); pv_one<3>(o[3], vb, pa0, pa1, pa2, pa3);
	v_mfma_f32_32x32x16_bf16 v[0:15], v[148:151], v[228:231], v[0:15]
	ds_read_b64_tr_b16 v[228:229], v182 offset:0x200
	ds_read_b64_tr_b16 v[230:231], v182 offset:0xa00
	v_mfma_f32_32x32x16_bf16 v[0:15], v[152:155], v[232:235], v[0:15]
	ds_read_b64_tr_b16 v[232:233], v182 offset:0x1200
	ds_read_b64_tr_b16 v[234:235], v182 offset:0x1a00
	v_mfma_f32_32x32x16_bf16 v[0:15], v[220:223], v[236:239], v[0:15]
	ds_read_b64_tr_b16 v[236:237], v182 offset:0x2200
	ds_read_b64_tr_b16 v[238:239], v182 offset:0x2a00
	v_mfma_f32_32x32x16_bf16 v[0:15], v[224:227], v[244:247], v[0:15]
	ds_read_b64_tr_b16 v[244:245], v182 offset:0x3200
	ds_read_b64_tr_b16 v[246:247], v182 offset:0x3a00
	s_waitcnt lgkmcnt(0)
	v_mfma_f32_32x32x16_bf16 v[48:63], v[148:151], v[228:231], v[48:63]
	ds_read_b64_tr_b16 v[228:229], v182 offset:0x400
	ds_read_b64_tr_b16 v[230:231], v182 offset:0xc00
	v_mfma_f32_32x32x16_bf16 v[48:63], v[152:155], v[232:235], v[48:63]
	ds_read_b64_tr_b16 v[232:233], v182 offset:0x1400
	ds_read_b64_tr_b16 v[234:235], v182 offset:0x1c00
	v_mfma_f32_32x32x16_bf16 v[48:63], v[220:223], v[236:239], v[48:63]
	ds_read_b64_tr_b16 v[236:237], v182 offset:0x2400
	ds_read_b64_tr_b16 v[238:239], v182 offset:0x2c00
	v_mfma_f32_32x32x16_bf16 v[48:63], v[224:227], v[244:247], v[48:63]
	ds_read_b64_tr_b16 v[244:245], v182 offset:0x3400
	ds_read_b64_tr_b16 v[246:247], v182 offset:0x3c00
	s_waitcnt lgkmcnt(0)
	v_mfma_f32_32x32x16_bf16 v[32:47], v[148:151], v[228:231], v[32:47]
	ds_read_b64_tr_b16 v[228:229], v182 offset:0x600
	ds_read_b64_tr_b16 v[230:231], v182 offset:0xe00
	v_mfma_f32_32x32x16_bf16 v[32:47], v[152:155], v[232:235], v[32:47]
	ds_read_b64_tr_b16 v[232:233], v182 offset:0x1600
	ds_read_b64_tr_b16 v[234:235], v182 offset:0x1e00
	v_mfma_f32_32x32x16_bf16 v[32:47], v[220:223], v[236:239], v[32:47]
	ds_read_b64_tr_b16 v[236:237], v182 offset:0x2600
	ds_read_b64_tr_b16 v[238:239], v182 offset:0x2e00
	v_mfma_f32_32x32x16_bf16 v[32:47], v[224:227], v[244:247], v[32:47]
	ds_read_b64_tr_b16 v[244:245], v182 offset:0x3600
	ds_read_b64_tr_b16 v[246:247], v182 offset:0x3e00
	s_waitcnt lgkmcnt(0)
	v_mfma_f32_32x32x16_bf16 v[16:31], v[148:151], v[228:231], v[16:31]
	v_max_f32_e32 v148, v80, v81
	v_max3_f32 v148, v148, v82, v83
	v_max3_f32 v148, v148, v84, v85
	v_max3_f32 v148, v148, v86, v87
	v_max3_f32 v148, v148, v88, v89
	v_max3_f32 v148, v148, v90, v91
	v_max3_f32 v148, v148, v92, v93
	v_mfma_f32_32x32x16_bf16 v[16:31], v[152:155], v[232:235], v[16:31]
	v_max3_f32 v148, v148, v94, v95
	v_max3_f32 v148, v148, v64, v65
	v_max3_f32 v148, v148, v66, v67
	v_max3_f32 v148, v148, v68, v69
	v_max3_f32 v148, v148, v70, v71
	v_max3_f32 v148, v148, v72, v73
	v_max3_f32 v148, v148, v74, v75
	v_max3_f32 v148, v148, v76, v77
	v_mfma_f32_32x32x16_bf16 v[16:31], v[220:223], v[236:239], v[16:31]
	v_max3_f32 v148, v148, v78, v79
	v_mov_b32_e32 v149, v148
	s_nop 1
	v_permlane32_swap_b32_e32 v148, v149
	v_max_f32_e32 v148, v148, v149
	v_sub_f32_e32 v149, v148, v210
	v_cmp_ge_f32_e32 vcc, s69, v149
	v_mfma_f32_32x32x16_bf16 v[16:31], v[224:227], v[244:247], v[16:31]
	s_cmp_eq_u64 vcc, exec
	s_cselect_b64 s[8:9], -1, 0
	s_cbranch_scc1 .Lafast_3
	v_max_f32_e32 v148, v210, v148
	v_sub_f32_e32 v149, v210, v148
	v_mul_f32_e32 v149, 0x3dd53b94, v149
	v_exp_f32_e32 v149, v149
	s_barrier
	s_waitcnt vmcnt(0)
	v_cndmask_b32_e64 v219, v149, 1.0, s[8:9]
	v_cmp_gt_f32_e32 vcc, 1.0, v219
	ds_write_b128 v184, v[128:131]
	ds_write_b128 v185, v[132:135]
	ds_write_b128 v189, v[136:139] offset:32768
	ds_write_b128 v189, v[140:143] offset:45056
	ds_write_b128 v191, v[144:147] offset:32768
	s_cbranch_vccz .LBB0_952
	s_and_saveexec_b64 s[12:13], s[6:7]
	ds_write_b32 v179, v219 offset:128
	s_or_b64 exec, exec, s[12:13]
	s_waitcnt lgkmcnt(0)
	v_add_u32_e32 v140, s59, v192
	ds_read_b128 v[128:131], v140 offset:224
	ds_read_b128 v[132:135], v140 offset:192
	ds_read_b128 v[136:139], v140 offset:160
	ds_read_b128 v[140:143], v140 offset:128
	s_waitcnt lgkmcnt(3)
	v_pk_mul_f32 v[12:13], v[12:13], v[128:129]
	s_waitcnt lgkmcnt(2)
	v_pk_mul_f32 v[8:9], v[8:9], v[132:133]
	s_waitcnt lgkmcnt(1)
	v_pk_mul_f32 v[4:5], v[4:5], v[136:137]
	v_pk_mul_f32 v[14:15], v[14:15], v[130:131]
	v_pk_mul_f32 v[10:11], v[10:11], v[134:135]
	v_pk_mul_f32 v[6:7], v[6:7], v[138:139]
	s_waitcnt lgkmcnt(0)
	v_pk_mul_f32 v[2:3], v[2:3], v[142:143]
	v_pk_mul_f32 v[0:1], v[0:1], v[140:141]
	v_pk_mul_f32 v[60:61], v[60:61], v[128:129]
	v_pk_mul_f32 v[56:57], v[56:57], v[132:133]
	v_pk_mul_f32 v[52:53], v[52:53], v[136:137]
	v_pk_mul_f32 v[62:63], v[62:63], v[130:131]
	v_pk_mul_f32 v[58:59], v[58:59], v[134:135]
	v_pk_mul_f32 v[54:55], v[54:55], v[138:139]
	v_pk_mul_f32 v[50:51], v[50:51], v[142:143]
	v_pk_mul_f32 v[48:49], v[48:49], v[140:141]
	v_pk_mul_f32 v[44:45], v[44:45], v[128:129]
	v_pk_mul_f32 v[40:41], v[40:41], v[132:133]
	v_pk_mul_f32 v[36:37], v[36:37], v[136:137]
	v_pk_mul_f32 v[46:47], v[46:47], v[130:131]
	v_pk_mul_f32 v[42:43], v[42:43], v[134:135]
	v_pk_mul_f32 v[38:39], v[38:39], v[138:139]
	v_pk_mul_f32 v[34:35], v[34:35], v[142:143]
	v_pk_mul_f32 v[32:33], v[32:33], v[140:141]
	v_pk_mul_f32 v[28:29], v[28:29], v[128:129]
	v_pk_mul_f32 v[24:25], v[24:25], v[132:133]
	v_pk_mul_f32 v[20:21], v[20:21], v[136:137]
	v_pk_mul_f32 v[30:31], v[30:31], v[130:131]
	v_pk_mul_f32 v[26:27], v[26:27], v[134:135]
	v_pk_mul_f32 v[22:23], v[22:23], v[138:139]
	v_pk_mul_f32 v[18:19], v[18:19], v[142:143]
	v_pk_mul_f32 v[16:17], v[16:17], v[140:141]
.LBB0_952:
	v_cndmask_b32_e64 v210, v148, v210, s[8:9]
	s_branch .Lajoin_3
; #define SBAR() __builtin_amdgcn_sched_barrier(0)
; template <int DK>
; __device__ __forceinline__ void partialSM(f32x16& p0, f32x16& p1, float& m_reg, float& mn, float& alpha) {
;     ...
;   float mnC = -mn * C;
; #pragma unroll
;   for (int r = 0; r < 16; ++r) p0[r] = fmaf(p0[r], C, mnC);
; #pragma unroll
;   for (int r = 0; r < 16; ++r) p1[r] = fmaf(p1[r], C, mnC);
; #pragma unroll
;   for (int r = 0; r < 16; ++r) p0[r] = __builtin_amdgcn_exp2f(p0[r]);
; }
; template <int DK, int NPARK>
; __device__ __forceinline__ void qkt(f32x16& p0, f32x16& p1, const char* Ks, const bf16x8* qr, const char* qpark, int r32, int hi) {
;   p0 = f32x16{}; p1 = f32x16{};
; #pragma unroll
;   for (int d0 = 0; d0 < DK / 16; ++d0) { const int cb = (d0 * 16 + hi * 8) * 2;
;     bf16x8 b0 = *reinterpret_cast<const bf16x8*>(Ks + kswz<DK>(r32, cb));
;     bf16x8 b1 = *reinterpret_cast<const bf16x8*>(Ks + kswz<DK>(32 + r32, cb));
;     bf16x8 q;
;     if constexpr (NPARK > 0) { if (d0 >= DK / 16 - NPARK) q = *reinterpret_cast<const bf16x8*>(qpark + (d0 - (DK / 16 - NPARK)) * 1024); else q = qr[d0]; } else q = qr[d0];
;     p0 = __builtin_amdgcn_mfma_f32_32x32x16_bf16(b0, q, p0, 0, 0, 0);
;     p1 = __builtin_amdgcn_mfma_f32_32x32x16_bf16(b1, q, p1, 0, 0, 0); }
; }
; template <int DK, int LDQ, int LDK, int LDV, int LDO, int SDEPTH, int NPARK>
; __device__ __forceinline__ void body(const bf16_t* __restrict__ Qb, const bf16_t* __restrict__ Kh, const bf16_t* __restrict__ Vh, bf16_t* __restrict__ Ob, int seq, char* lds, int tid, int wid) {
;     ...
;     SBAR(); qkt<DK, NPARK>(pA0, pA1, K_lds, qr, qpark, r32, hi);
;     finishSM(pB0, pB1, alB, l_reg, pa0, pa1, pa2, pa3); SBAR();
.Lafast_3:
	s_barrier
	s_waitcnt vmcnt(0)
	v_mov_b32_e32 v219, 1.0
	ds_write_b128 v184, v[128:131]
	ds_write_b128 v185, v[132:135]
	ds_write_b128 v189, v[136:139] offset:32768
	ds_write_b128 v189, v[140:143] offset:45056
	ds_write_b128 v191, v[144:147] offset:32768
.Lajoin_3:
	v_mul_f32_e32 v144, 0xbdd53b94, v210
	v_pk_fma_f32 v[80:81], v[80:81], s[78:79], v[144:145] op_sel_hi:[1,0,0]
	v_pk_fma_f32 v[82:83], v[82:83], s[78:79], v[144:145] op_sel_hi:[1,0,0]
	v_pk_fma_f32 v[84:85], v[84:85], s[78:79], v[144:145] op_sel_hi:[1,0,0]
	v_pk_fma_f32 v[86:87], v[86:87], s[78:79], v[144:145] op_sel_hi:[1,0,0]
	v_pk_fma_f32 v[88:89], v[88:89], s[78:79], v[144:145] op_sel_hi:[1,0,0]
	v_pk_fma_f32 v[90:91], v[90:91], s[78:79], v[144:145] op_sel_hi:[1,0,0]
	v_pk_fma_f32 v[92:93], v[92:93], s[78:79], v[144:145] op_sel_hi:[1,0,0]
	v_pk_fma_f32 v[94:95], v[94:95], s[78:79], v[144:145] op_sel_hi:[1,0,0]
	v_fmamk_f32 v220, v67, 0x3dd53b94, v144
	v_fmamk_f32 v221, v68, 0x3dd53b94, v144
	v_fmamk_f32 v148, v71, 0x3dd53b94, v144
	v_fmamk_f32 v149, v72, 0x3dd53b94, v144
	v_fmamk_f32 v153, v64, 0x3dd53b94, v144
	v_fmamk_f32 v154, v65, 0x3dd53b94, v144
	v_fmamk_f32 v155, v66, 0x3dd53b94, v144
	v_fmamk_f32 v146, v69, 0x3dd53b94, v144
	v_fmamk_f32 v147, v70, 0x3dd53b94, v144
	v_fmamk_f32 v150, v73, 0x3dd53b94, v144
	v_fmamk_f32 v151, v74, 0x3dd53b94, v144
	v_fmamk_f32 v152, v75, 0x3dd53b94, v144
	v_fmamk_f32 v145, v76, 0x3dd53b94, v144
	v_exp_f32_e32 v141, v80
	v_exp_f32_e32 v143, v81
	v_exp_f32_e32 v139, v82
	v_exp_f32_e32 v142, v83
	v_exp_f32_e32 v138, v84
	v_exp_f32_e32 v140, v85
	v_exp_f32_e32 v136, v86
	v_exp_f32_e32 v137, v87
	v_exp_f32_e32 v133, v88
	v_exp_f32_e32 v135, v89
	v_exp_f32_e32 v132, v90
	v_exp_f32_e32 v134, v91
	v_exp_f32_e32 v129, v92
	v_exp_f32_e32 v131, v93
	v_exp_f32_e32 v128, v94
	v_exp_f32_e32 v130, v95
	v_fmamk_f32 v222, v77, 0x3dd53b94, v144
	v_fmamk_f32 v223, v78, 0x3dd53b94, v144
	v_fmac_f32_e32 v144, 0x3dd53b94, v79
	s_waitcnt lgkmcnt(0)
	s_barrier
	ds_read_b128 v[64:67], v196 offset:32768
	ds_read_b128 v[68:71], v196 offset:45056
	ds_read_b128 v[224:227], v199 offset:32768
	ds_read_b128 v[228:231], v199 offset:45056
	v_exp_f32_e32 v146, v146
	v_exp_f32_e32 v147, v147
	s_waitcnt lgkmcnt(3)
	v_mfma_f32_32x32x16_bf16 v[80:95], v[64:67], v[124:127], 0
	v_exp_f32_e32 v145, v145
	v_exp_f32_e32 v144, v144
	s_waitcnt lgkmcnt(2)
	v_mfma_f32_32x32x16_bf16 v[64:79], v[68:71], v[124:127], 0
	s_waitcnt lgkmcnt(0)
	v_mfma_f32_32x32x16_bf16 v[64:79], v[228:231], v[116:119], v[64:79]
	v_mfma_f32_32x32x16_bf16 v[80:95], v[224:227], v[116:119], v[80:95]
	ds_read_b128 v[224:227], v198 offset:32768
	ds_read_b128 v[228:231], v198 offset:45056
	s_waitcnt lgkmcnt(0)
	v_mfma_f32_32x32x16_bf16 v[64:79], v[228:231], v[120:123], v[64:79]
	v_mfma_f32_32x32x16_bf16 v[80:95], v[224:227], v[120:123], v[80:95]
	ds_read_b128 v[224:227], v197 offset:32768
	ds_read_b128 v[228:231], v197 offset:45056
	s_waitcnt lgkmcnt(0)
	v_mfma_f32_32x32x16_bf16 v[64:79], v[228:231], v[112:115], v[64:79]
	v_mfma_f32_32x32x16_bf16 v[80:95], v[224:227], v[112:115], v[80:95]
	ds_read_b128 v[224:227], v195 offset:32768
	ds_read_b128 v[228:231], v195 offset:45056
	s_waitcnt lgkmcnt(0)
	v_mfma_f32_32x32x16_bf16 v[64:79], v[228:231], v[108:111], v[64:79]
	v_mfma_f32_32x32x16_bf16 v[80:95], v[224:227], v[108:111], v[80:95]
	ds_read_b128 v[224:227], v194 offset:32768
	ds_read_b128 v[228:231], v194 offset:45056
	s_waitcnt lgkmcnt(0)
	v_mfma_f32_32x32x16_bf16 v[64:79], v[228:231], v[104:107], v[64:79]
	v_mfma_f32_32x32x16_bf16 v[80:95], v[224:227], v[104:107], v[80:95]
	ds_read_b128 v[224:227], v188 offset:32768
	ds_read_b128 v[228:231], v188 offset:45056
	s_waitcnt lgkmcnt(0)
	v_mfma_f32_32x32x16_bf16 v[64:79], v[228:231], v[100:103], v[64:79]
	v_mfma_f32_32x32x16_bf16 v[80:95], v[224:227], v[100:103], v[80:95]
	ds_read_b128 v[224:227], v187 offset:32768
	ds_read_b128 v[228:231], v187 offset:45056
	s_waitcnt lgkmcnt(0)
	v_mfma_f32_32x32x16_bf16 v[64:79], v[228:231], v[96:99], v[64:79]
	v_mfma_f32_32x32x16_bf16 v[80:95], v[224:227], v[96:99], v[80:95]
	ds_read_b128 v[224:227], v186 offset:32768
	ds_read_b128 v[228:231], v186 offset:45056
	ds_read_b128 v[232:235], v183
	s_waitcnt lgkmcnt(0)
	v_mfma_f32_32x32x16_bf16 v[64:79], v[228:231], v[232:235], v[64:79]
	v_mfma_f32_32x32x16_bf16 v[80:95], v[224:227], v[232:235], v[80:95]
	ds_read_b128 v[224:227], v190 offset:32768
	ds_read_b128 v[228:231], v190 offset:45056
	ds_read_b128 v[232:235], v183 offset:1024
	s_waitcnt lgkmcnt(0)
	v_mfma_f32_32x32x16_bf16 v[64:79], v[228:231], v[232:235], v[64:79]
	v_mfma_f32_32x32x16_bf16 v[80:95], v[224:227], v[232:235], v[80:95]
	ds_read_b128 v[224:227], v201 offset:32768
	ds_read_b128 v[228:231], v201 offset:45056
	ds_read_b128 v[232:235], v183 offset:2048
	s_waitcnt lgkmcnt(0)
	v_mfma_f32_32x32x16_bf16 v[64:79], v[228:231], v[232:235], v[64:79]
	v_mfma_f32_32x32x16_bf16 v[80:95], v[224:227], v[232:235], v[80:95]
	ds_read_b128 v[224:227], v200 offset:32768
	ds_read_b128 v[228:231], v200 offset:45056
	ds_read_b128 v[232:235], v183 offset:3072
	s_waitcnt lgkmcnt(0)
; __device__ __forceinline__ void finishSM(f32x16& p0, f32x16& p1, float alpha, float& l_reg, bf16x8& pa0, bf16x8& pa1, bf16x8& pa2, bf16x8& pa3) {
; #pragma unroll
;   for (int r = 0; r < 16; ++r) p1[r] = __builtin_amdgcn_exp2f(p1[r]);
;   float ps = 0;
; #pragma unroll
;   for (int r = 0; r < 16; ++r) ps += p0[r];
; #pragma unroll
;   for (int r = 0; r < 16; ++r) ps += p1[r];
;   { auto rr = __builtin_amdgcn_permlane32_swap(__float_as_uint(ps), __float_as_uint(ps), false, false);
;     ps = __uint_as_float(rr[0]) + __uint_as_float(rr[1]); }
;   l_reg = l_reg * alpha + ps;
;     ...
;   PK4(p0, 0, pa0); PK4(p0, 8, pa1); PK4(p1, 0, pa2); PK4(p1, 8, pa3);
;     ...
; }
; template <int DK, int NPARK>
; __device__ __forceinline__ void qkt(f32x16& p0, f32x16& p1, const char* Ks, const bf16x8* qr, const char* qpark, int r32, int hi) {
;   p0 = f32x16{}; p1 = f32x16{};
; #pragma unroll
;   for (int d0 = 0; d0 < DK / 16; ++d0) { const int cb = (d0 * 16 + hi * 8) * 2;
;     bf16x8 b0 = *reinterpret_cast<const bf16x8*>(Ks + kswz<DK>(r32, cb));
;     bf16x8 b1 = *reinterpret_cast<const bf16x8*>(Ks + kswz<DK>(32 + r32, cb));
;     bf16x8 q;
;     if constexpr (NPARK > 0) { if (d0 >= DK / 16 - NPARK) q = *reinterpret_cast<const bf16x8*>(qpark + (d0 - (DK / 16 - NPARK)) * 1024); else q = qr[d0]; } else q = qr[d0];
;     p0 = __builtin_amdgcn_mfma_f32_32x32x16_bf16(b0, q, p0, 0, 0, 0);
;     p1 = __builtin_amdgcn_mfma_f32_32x32x16_bf16(b1, q, p1, 0, 0, 0); }
; }
; __device__ __forceinline__ int v_st(int k, int c) { const int kk = (k & ~0xC) | ((k & 4) << 1) | ((k & 8) >> 1); return ((kk >> 3) * 4 + (c >> 5)) * 512 + ((kk & 7) * 32 + (c & 31)) * 2; }
; __device__ __forceinline__ int v_rd_base(int lane) { return ((lane & 3) << 3) | (((lane >> 2) & 3) << 6) | (((lane >> 4) & 1) << 5) | (((lane >> 5) & 1) << 8); }
; template <int OFF> __device__ __forceinline__ s16x4 tr_read(int vb) {
;   s16x4 r; asm volatile("ds_read_b64_tr_b16 %0, %1 offset:%2" : "=&v"(r) : "v"(vb), "i"(OFF) : "memory"); return r;
; }
; template <int D0> __device__ __forceinline__ void pv_one(f32x16& od, int vb, bf16x8 pa0, bf16x8 pa1, bf16x8 pa2, bf16x8 pa3) {
;   const s16x4 l0 = tr_read<v_rd_off(D0, 0, 0)>(vb), h0 = tr_read<v_rd_off(D0, 0, 1)>(vb), l1 = tr_read<v_rd_off(D0, 1, 0)>(vb), h1 = tr_read<v_rd_off(D0, 1, 1)>(vb);
	v_mfma_f32_32x32x16_bf16 v[64:79], v[228:231], v[232:235], v[64:79]
	v_exp_f32_e32 v229, v148
	v_add_f32_e32 v148, v143, v141
	v_add_f32_e32 v148, v139, v148
	v_add_f32_e32 v148, v142, v148
	v_add_f32_e32 v148, v138, v148
	v_add_f32_e32 v148, v140, v148
	v_add_f32_e32 v148, v136, v148
	v_add_f32_e32 v148, v137, v148
	v_add_f32_e32 v148, v133, v148
	v_add_f32_e32 v148, v135, v148
	v_add_f32_e32 v148, v132, v148
	v_add_f32_e32 v148, v134, v148
	v_mfma_f32_32x32x16_bf16 v[80:95], v[224:227], v[232:235], v[80:95]
	v_exp_f32_e32 v224, v153
	v_add_f32_e32 v148, v129, v148
	v_exp_f32_e32 v225, v154
	v_add_f32_e32 v148, v131, v148
	v_exp_f32_e32 v226, v155
	v_add_f32_e32 v148, v128, v148
	v_exp_f32_e32 v227, v220
	v_add_f32_e32 v148, v130, v148
	v_exp_f32_e32 v228, v221
	v_add_f32_e32 v148, v224, v148
	v_add_f32_e32 v148, v225, v148
	v_add_f32_e32 v148, v226, v148
	v_add_f32_e32 v148, v227, v148
	v_exp_f32_e32 v230, v149
	v_add_f32_e32 v148, v228, v148
	v_exp_f32_e32 v231, v150
	v_add_f32_e32 v148, v146, v148
	v_exp_f32_e32 v232, v151
	v_add_f32_e32 v148, v147, v148
	v_exp_f32_e32 v233, v152
	v_add_f32_e32 v148, v229, v148
	v_add_f32_e32 v148, v230, v148
	v_exp_f32_e32 v234, v222
	v_add_f32_e32 v148, v231, v148
	v_exp_f32_e32 v235, v223
	v_add_f32_e32 v148, v232, v148
	v_add_f32_e32 v148, v233, v148
	v_add_f32_e32 v148, v145, v148
	v_add_f32_e32 v148, v234, v148
	v_add_f32_e32 v148, v235, v148
	v_add_f32_e32 v220, v144, v148
	v_mov_b32_e32 v221, v220
	v_cvt_pk_bf16_f32 v148, v141, v143
	v_cvt_pk_bf16_f32 v149, v139, v142
	v_cvt_pk_bf16_f32 v150, v138, v140
	v_cvt_pk_bf16_f32 v151, v136, v137
	s_nop 1
	v_permlane32_swap_b32_e32 v220, v221
	v_permlane32_swap_b32_e32 v148, v150
	v_permlane32_swap_b32_e32 v149, v151
	v_cvt_pk_bf16_f32 v152, v133, v135
	v_cvt_pk_bf16_f32 v153, v132, v134
	v_cvt_pk_bf16_f32 v154, v129, v131
	v_cvt_pk_bf16_f32 v155, v128, v130
	v_cvt_pk_bf16_f32 v222, v224, v225
	v_cvt_pk_bf16_f32 v223, v226, v227
	v_cvt_pk_bf16_f32 v224, v228, v146
	v_cvt_pk_bf16_f32 v225, v147, v229
	v_cvt_pk_bf16_f32 v226, v230, v231
	v_cvt_pk_bf16_f32 v227, v232, v233
	v_cvt_pk_bf16_f32 v228, v145, v234
	v_cvt_pk_bf16_f32 v229, v235, v144
	s_nop 0
	v_permlane32_swap_b32_e32 v152, v154
	v_permlane32_swap_b32_e32 v153, v155
	v_permlane32_swap_b32_e32 v222, v224
	v_permlane32_swap_b32_e32 v223, v225
	v_permlane32_swap_b32_e32 v226, v228
	v_permlane32_swap_b32_e32 v227, v229
	s_add_u32 s34, s32, s63
	s_addc_u32 s35, s33, 0
	s_add_u32 s36, s56, s82
	s_addc_u32 s37, s57, 0
	global_load_dwordx4 v[128:131], v251, s[34:35]
	global_load_dwordx4 v[132:135], v252, s[34:35]
	global_load_dwordx4 v[136:139], v248, s[36:37]
	global_load_dwordx4 v[140:143], v249, s[36:37]
	global_load_dwordx4 v[144:147], v250, s[36:37]
	ds_read_b64_tr_b16 v[168:169], v181 offset:0
	ds_read_b64_tr_b16 v[170:171], v181 offset:0x800
	ds_read_b64_tr_b16 v[172:173], v181 offset:0x1000
	ds_read_b64_tr_b16 v[174:175], v181 offset:0x1800
	ds_read_b64_tr_b16 v[230:231], v181 offset:0x2000
	ds_read_b64_tr_b16 v[232:233], v181 offset:0x2800
	ds_read_b64_tr_b16 v[234:235], v181 offset:0x3000
	ds_read_b64_tr_b16 v[236:237], v181 offset:0x3800
	s_waitcnt lgkmcnt(0)
	v_mfma_f32_32x32x16_bf16 v[0:15], v[148:151], v[168:171], v[0:15]
	ds_read_b64_tr_b16 v[168:169], v181 offset:0x200
	ds_read_b64_tr_b16 v[170:171], v181 offset:0xa00
	v_mfma_f32_32x32x16_bf16 v[0:15], v[152:155], v[172:175], v[0:15]
	ds_read_b64_tr_b16 v[172:173], v181 offset:0x1200
	ds_read_b64_tr_b16 v[174:175], v181 offset:0x1a00
	v_mfma_f32_32x32x16_bf16 v[0:15], v[222:225], v[230:233], v[0:15]
	ds_read_b64_tr_b16 v[230:231], v181 offset:0x2200
	ds_read_b64_tr_b16 v[232:233], v181 offset:0x2a00
	v_mfma_f32_32x32x16_bf16 v[0:15], v[226:229], v[234:237], v[0:15]
	ds_read_b64_tr_b16 v[234:235], v181 offset:0x3200
	ds_read_b64_tr_b16 v[236:237], v181 offset:0x3a00
	s_waitcnt lgkmcnt(0)
	v_mfma_f32_32x32x16_bf16 v[48:63], v[148:151], v[168:171], v[48:63]
	ds_read_b64_tr_b16 v[168:169], v181 offset:0x400
	ds_read_b64_tr_b16 v[170:171], v181 offset:0xc00
	v_mfma_f32_32x32x16_bf16 v[48:63], v[152:155], v[172:175], v[48:63]
	ds_read_b64_tr_b16 v[172:173], v181 offset:0x1400
	ds_read_b64_tr_b16 v[174:175], v181 offset:0x1c00
	v_mfma_f32_32x32x16_bf16 v[48:63], v[222:225], v[230:233], v[48:63]
	ds_read_b64_tr_b16 v[230:231], v181 offset:0x2400
	ds_read_b64_tr_b16 v[232:233], v181 offset:0x2c00
	v_mfma_f32_32x32x16_bf16 v[48:63], v[226:229], v[234:237], v[48:63]
	ds_read_b64_tr_b16 v[234:235], v181 offset:0x3400
	ds_read_b64_tr_b16 v[236:237], v181 offset:0x3c00
	s_waitcnt lgkmcnt(0)
	v_mfma_f32_32x32x16_bf16 v[32:47], v[148:151], v[168:171], v[32:47]
	ds_read_b64_tr_b16 v[168:169], v181 offset:0x600
	ds_read_b64_tr_b16 v[170:171], v181 offset:0xe00
	v_mfma_f32_32x32x16_bf16 v[32:47], v[152:155], v[172:175], v[32:47]
	ds_read_b64_tr_b16 v[172:173], v181 offset:0x1600
	ds_read_b64_tr_b16 v[174:175], v181 offset:0x1e00
	v_mfma_f32_32x32x16_bf16 v[32:47], v[222:225], v[230:233], v[32:47]
	ds_read_b64_tr_b16 v[230:231], v181 offset:0x2600
	ds_read_b64_tr_b16 v[232:233], v181 offset:0x2e00
	v_mfma_f32_32x32x16_bf16 v[32:47], v[226:229], v[234:237], v[32:47]
	ds_read_b64_tr_b16 v[234:235], v181 offset:0x3600
	ds_read_b64_tr_b16 v[236:237], v181 offset:0x3e00
	s_waitcnt lgkmcnt(0)
	v_mfma_f32_32x32x16_bf16 v[16:31], v[148:151], v[168:171], v[16:31]
	v_max_f32_e32 v148, v80, v81
	v_max3_f32 v148, v148, v82, v83
	v_max3_f32 v148, v148, v84, v85
	v_max3_f32 v148, v148, v86, v87
	v_max3_f32 v148, v148, v88, v89
	v_max3_f32 v148, v148, v90, v91
	v_max3_f32 v148, v148, v92, v93
	v_mfma_f32_32x32x16_bf16 v[16:31], v[152:155], v[172:175], v[16:31]
	v_max3_f32 v148, v148, v94, v95
	v_max3_f32 v148, v148, v64, v65
	v_max3_f32 v148, v148, v66, v67
	v_max3_f32 v148, v148, v68, v69
	v_max3_f32 v148, v148, v70, v71
	v_max3_f32 v148, v148, v72, v73
	v_max3_f32 v148, v148, v74, v75
	v_max3_f32 v148, v148, v76, v77
	v_mfma_f32_32x32x16_bf16 v[16:31], v[222:225], v[230:233], v[16:31]
	v_max3_f32 v148, v148, v78, v79
	v_mov_b32_e32 v149, v148
	s_nop 1
	v_permlane32_swap_b32_e32 v148, v149
	v_max_f32_e32 v148, v148, v149
	v_sub_f32_e32 v149, v148, v210
	v_cmp_ge_f32_e32 vcc, s69, v149
	v_mfma_f32_32x32x16_bf16 v[16:31], v[226:229], v[234:237], v[16:31]
	s_cmp_eq_u64 vcc, exec
	s_cselect_b64 s[8:9], -1, 0
	s_cbranch_scc1 .Lafast_4
; #define SBAR() __builtin_amdgcn_sched_barrier(0)
; #define SWAIT() do { if constexpr (SDEPTH == 2) { if constexpr (DK == 192) asm volatile("s_waitcnt vmcnt(5)" ::: "memory"); else asm volatile("s_waitcnt vmcnt(4)" ::: "memory"); } else asm volatile("s_waitcnt vmcnt(0)" ::: "memory"); } while (0)
; #define RESC(a) do { if (__any((a) < 1.f)) { if (hi == 0) al_l[r32] = (a); asm volatile("s_waitcnt lgkmcnt(0)" ::: "memory"); \
;     _Pragma("unroll") for (int d = 0; d < 4; ++d) _Pragma("unroll") for (int r = 0; r < 16; ++r) o[d][r] *= al_l[crow(r, hi)]; } } while (0)
; template <int DK>
; __device__ __forceinline__ void partialSM(f32x16& p0, f32x16& p1, float& m_reg, float& mn, float& alpha) {
;   constexpr float SCALE = Cst<DK>::SCALE, C = SCALE * 1.4426950408889634f;
;   float pmax = p0[0];
; #pragma unroll
;   for (int r = 1; r < 16; ++r) pmax = fmaxf(pmax, p0[r]);
; #pragma unroll
;   for (int r = 0; r < 16; ++r) pmax = fmaxf(pmax, p1[r]);
;   { auto rr = __builtin_amdgcn_permlane32_swap(__float_as_uint(pmax), __float_as_uint(pmax), false, false);
;     pmax = fmaxf(__uint_as_float(rr[0]), __uint_as_float(rr[1])); }
;   if (__builtin_expect(__all(pmax - m_reg <= THR / SCALE), 1)) { mn = m_reg; alpha = 1.f; }
;   else { mn = fmaxf(m_reg, pmax); alpha = __builtin_amdgcn_exp2f((m_reg - mn) * C); m_reg = mn; }
;   float mnC = -mn * C;
; #pragma unroll
;   for (int r = 0; r < 16; ++r) p0[r] = fmaf(p0[r], C, mnC);
; #pragma unroll
;   for (int r = 0; r < 16; ++r) p1[r] = fmaf(p1[r], C, mnC);
; #pragma unroll
;   for (int r = 0; r < 16; ++r) p0[r] = __builtin_amdgcn_exp2f(p0[r]);
; }
; template <int DK, int LDQ, int LDK, int LDV, int LDO, int SDEPTH, int NPARK>
; __device__ __forceinline__ void body(const bf16_t* __restrict__ Qb, const bf16_t* __restrict__ Kh, const bf16_t* __restrict__ Vh, bf16_t* __restrict__ Ob, int seq, char* lds, int tid, int wid) {
;     ...
;     __syncthreads(); SWAIT(); SWRITE(0, SE);
;     RESC(alB); __syncthreads();
;     SBAR(); qkt<DK, NPARK>(pA0, pA1, K_lds, qr, qpark, r32, hi);
;     finishSM(pB0, pB1, alB, l_reg, pa0, pa1, pa2, pa3); SBAR();
;     if (SDEPTH == 1 || j + 3 < NT) SLOAD(SE, (j + 1 + SDEPTH) * KVBLK); SBAR();
;     pv_d0(o, vb0 + (int)SHM_V, pa0, pa1, pa2, pa3); partialSM<DK>(pA0, pA1, m_reg, mnA, alA);
;     __syncthreads(); SWAIT(); SWRITE(1, SO);
;     RESC(alA); __syncthreads();
	v_max_f32_e32 v149, v210, v148
	v_sub_f32_e32 v148, v210, v149
	v_mul_f32_e32 v148, 0x3dd53b94, v148
	v_exp_f32_e32 v148, v148
	s_barrier
	s_waitcnt vmcnt(0)
	v_cndmask_b32_e64 v148, v148, 1.0, s[8:9]
	v_cmp_gt_f32_e32 vcc, 1.0, v148
	ds_write_b128 v184, v[128:131] offset:16384
	ds_write_b128 v185, v[132:135] offset:16384
	ds_write_b128 v189, v[136:139] offset:57344
	ds_write_b128 v202, v[140:143] offset:57344
	ds_write_b128 v191, v[144:147] offset:57344
	s_cbranch_vccz .LBB0_956
	s_and_saveexec_b64 s[12:13], s[6:7]
	ds_write_b32 v179, v148 offset:128
	s_or_b64 exec, exec, s[12:13]
	s_waitcnt lgkmcnt(0)
	v_add_u32_e32 v140, s59, v192
	ds_read_b128 v[128:131], v140 offset:224
	ds_read_b128 v[132:135], v140 offset:192
	ds_read_b128 v[136:139], v140 offset:160
	ds_read_b128 v[140:143], v140 offset:128
	s_waitcnt lgkmcnt(3)
	v_pk_mul_f32 v[12:13], v[12:13], v[128:129]
	s_waitcnt lgkmcnt(2)
	v_pk_mul_f32 v[8:9], v[8:9], v[132:133]
	s_waitcnt lgkmcnt(1)
	v_pk_mul_f32 v[4:5], v[4:5], v[136:137]
	v_pk_mul_f32 v[14:15], v[14:15], v[130:131]
	v_pk_mul_f32 v[10:11], v[10:11], v[134:135]
	v_pk_mul_f32 v[6:7], v[6:7], v[138:139]
	s_waitcnt lgkmcnt(0)
	v_pk_mul_f32 v[2:3], v[2:3], v[142:143]
	v_pk_mul_f32 v[0:1], v[0:1], v[140:141]
	v_pk_mul_f32 v[60:61], v[60:61], v[128:129]
	v_pk_mul_f32 v[56:57], v[56:57], v[132:133]
	v_pk_mul_f32 v[52:53], v[52:53], v[136:137]
	v_pk_mul_f32 v[62:63], v[62:63], v[130:131]
	v_pk_mul_f32 v[58:59], v[58:59], v[134:135]
	v_pk_mul_f32 v[54:55], v[54:55], v[138:139]
	v_pk_mul_f32 v[50:51], v[50:51], v[142:143]
	v_pk_mul_f32 v[48:49], v[48:49], v[140:141]
	v_pk_mul_f32 v[44:45], v[44:45], v[128:129]
	v_pk_mul_f32 v[40:41], v[40:41], v[132:133]
	v_pk_mul_f32 v[36:37], v[36:37], v[136:137]
	v_pk_mul_f32 v[46:47], v[46:47], v[130:131]
	v_pk_mul_f32 v[42:43], v[42:43], v[134:135]
	v_pk_mul_f32 v[38:39], v[38:39], v[138:139]
	v_pk_mul_f32 v[34:35], v[34:35], v[142:143]
	v_pk_mul_f32 v[32:33], v[32:33], v[140:141]
	v_pk_mul_f32 v[28:29], v[28:29], v[128:129]
	v_pk_mul_f32 v[24:25], v[24:25], v[132:133]
	v_pk_mul_f32 v[20:21], v[20:21], v[136:137]
	v_pk_mul_f32 v[30:31], v[30:31], v[130:131]
	v_pk_mul_f32 v[26:27], v[26:27], v[134:135]
	v_pk_mul_f32 v[22:23], v[22:23], v[138:139]
	v_pk_mul_f32 v[18:19], v[18:19], v[142:143]
	v_pk_mul_f32 v[16:17], v[16:17], v[140:141]
.LBB0_956:
	v_cndmask_b32_e64 v210, v149, v210, s[8:9]
	s_branch .Lajoin_4
.Lafast_4:
	s_barrier
	s_waitcnt vmcnt(0)
	v_mov_b32_e32 v148, 1.0
	ds_write_b128 v184, v[128:131] offset:16384
	ds_write_b128 v185, v[132:135] offset:16384
	ds_write_b128 v189, v[136:139] offset:57344
	ds_write_b128 v202, v[140:143] offset:57344
	ds_write_b128 v191, v[144:147] offset:57344
.Lajoin_4:
	v_mul_f32_e32 v128, 0xbdd53b94, v210
	v_pk_fma_f32 v[80:81], v[80:81], s[78:79], v[128:129] op_sel_hi:[1,0,0]
	v_pk_fma_f32 v[82:83], v[82:83], s[78:79], v[128:129] op_sel_hi:[1,0,0]
	v_pk_fma_f32 v[84:85], v[84:85], s[78:79], v[128:129] op_sel_hi:[1,0,0]
	v_pk_fma_f32 v[86:87], v[86:87], s[78:79], v[128:129] op_sel_hi:[1,0,0]
	v_pk_fma_f32 v[88:89], v[88:89], s[78:79], v[128:129] op_sel_hi:[1,0,0]
	v_pk_fma_f32 v[90:91], v[90:91], s[78:79], v[128:129] op_sel_hi:[1,0,0]
	v_pk_fma_f32 v[92:93], v[92:93], s[78:79], v[128:129] op_sel_hi:[1,0,0]
	v_pk_fma_f32 v[94:95], v[94:95], s[78:79], v[128:129] op_sel_hi:[1,0,0]
	v_exp_f32_e32 v149, v80
	v_exp_f32_e32 v170, v81
	v_exp_f32_e32 v150, v82
	v_exp_f32_e32 v171, v83
	v_exp_f32_e32 v169, v84
	v_exp_f32_e32 v172, v85
	v_exp_f32_e32 v151, v86
	v_exp_f32_e32 v168, v87
	v_exp_f32_e32 v147, v88
	v_exp_f32_e32 v152, v89
	v_exp_f32_e32 v153, v90
	v_exp_f32_e32 v154, v91
	v_exp_f32_e32 v144, v92
	v_exp_f32_e32 v145, v93
	v_exp_f32_e32 v146, v94
	v_exp_f32_e32 v155, v95
	v_pk_fma_f32 v[142:143], v[64:65], s[78:79], v[128:129] op_sel_hi:[1,0,0]
	v_add_f32_e32 v64, v217, v218
	v_fmac_f32_e32 v64, v215, v180
	v_add_f32_e32 v180, v220, v221
	s_add_i32 s14, s14, 2
	v_pk_fma_f32 v[140:141], v[66:67], s[78:79], v[128:129] op_sel_hi:[1,0,0]
	v_pk_fma_f32 v[136:137], v[68:69], s[78:79], v[128:129] op_sel_hi:[1,0,0]
	v_pk_fma_f32 v[132:133], v[70:71], s[78:79], v[128:129] op_sel_hi:[1,0,0]
	v_pk_fma_f32 v[130:131], v[72:73], s[78:79], v[128:129] op_sel_hi:[1,0,0]
	v_pk_fma_f32 v[138:139], v[74:75], s[78:79], v[128:129] op_sel_hi:[1,0,0]
	v_pk_fma_f32 v[134:135], v[76:77], s[78:79], v[128:129] op_sel_hi:[1,0,0]
	v_pk_fma_f32 v[128:129], v[78:79], s[78:79], v[128:129] op_sel_hi:[1,0,0]
	v_fmac_f32_e32 v180, v64, v219
	s_add_u32 s56, s56, 0x30000
	s_addc_u32 s57, s57, 0
	s_add_u32 s32, s32, 0x20000
	s_addc_u32 s33, s33, 0
	s_cmp_ge_u32 s14, s23
	s_waitcnt lgkmcnt(0)
	s_barrier
	s_cbranch_scc1 .LBB0_958
	v_mov_b32_e32 v215, v148
	s_branch .LBB0_948
